# v_combo19 + non-temporal hint on the streaming output stores of p2_conv, p4_yb and the scan
# speedup vs baseline: 1.0081x; 1.0032x over previous
.LBB0_298:
	s_or_b64 exec, exec, s[40:41]
	v_readlane_b32 s76, v247, 26
	v_readlane_b32 s84, v247, 34
	v_readlane_b32 s85, v247, 35
	v_readlane_b32 s86, v247, 36
	v_readlane_b32 s87, v247, 37
	v_readlane_b32 s88, v247, 38
	v_readlane_b32 s89, v247, 39
	s_mov_b64 s[52:53], s[84:85]
	v_lshlrev_b32_e32 v24, 2, v0
	s_mov_b64 s[54:55], s[86:87]
	s_mov_b64 s[56:57], s[88:89]
	global_load_dwordx4 v[32:35], v24, s[54:55]
	global_load_dwordx4 v[44:47], v24, s[56:57]
	global_load_dwordx4 v[36:39], v24, s[18:19]
	global_load_dwordx4 v[40:43], v24, s[24:25]
	global_load_dwordx4 v[0:3], v24, s[22:23]
	s_waitcnt vmcnt(55)
	v_lshlrev_b32_e32 v180, 16, v4
	v_and_b32_e32 v181, 0xffff0000, v4
	s_waitcnt vmcnt(52)
	v_lshlrev_b32_e32 v182, 16, v14
	v_and_b32_e32 v183, 0xffff0000, v14
	s_waitcnt vmcnt(49)
	v_lshlrev_b32_e32 v184, 16, v12
	v_and_b32_e32 v185, 0xffff0000, v12
	v_lshlrev_b32_e32 v186, 16, v5
	v_and_b32_e32 v187, 0xffff0000, v5
	v_lshlrev_b32_e32 v188, 16, v15
	v_and_b32_e32 v189, 0xffff0000, v15
	v_lshlrev_b32_e32 v190, 16, v13
	v_and_b32_e32 v191, 0xffff0000, v13
	s_waitcnt vmcnt(46)
	v_lshlrev_b32_e32 v192, 16, v10
	v_and_b32_e32 v193, 0xffff0000, v10
	v_lshlrev_b32_e32 v194, 16, v11
	v_and_b32_e32 v195, 0xffff0000, v11
	s_waitcnt vmcnt(43)
	v_lshlrev_b32_e32 v196, 16, v6
	v_and_b32_e32 v197, 0xffff0000, v6
	v_lshlrev_b32_e32 v198, 16, v7
	v_and_b32_e32 v199, 0xffff0000, v7
	s_waitcnt vmcnt(40)
	v_lshlrev_b32_e32 v200, 16, v8
	v_and_b32_e32 v201, 0xffff0000, v8
	v_lshlrev_b32_e32 v202, 16, v9
	v_and_b32_e32 v203, 0xffff0000, v9
	global_load_dwordx4 v[20:23], v24, s[14:15]
	global_load_dwordx4 v[16:19], v24, s[16:17]
	global_load_dwordx4 v[12:15], v24, s[20:21]
	global_load_dwordx4 v[8:11], v24, s[26:27]
	global_load_dwordx4 v[4:7], v24, s[34:35]
	global_load_dwordx4 v[28:31], v24, s[10:11]
	s_nop 0
	global_load_dwordx4 v[24:27], v24, s[12:13]
	v_or_b32_e32 v122, 1, v52
	v_mov_b32_e32 v123, s39
	v_mov_b32_e32 v129, v49
	v_lshlrev_b64 v[204:205], 11, v[122:123]
	v_or_b32_e32 v122, 2, v52
	v_lshl_add_u64 v[128:129], s[6:7], 0, v[128:129]
	v_lshlrev_b64 v[206:207], 11, v[122:123]
	v_or_b32_e32 v122, 3, v52
	v_lshl_add_u64 v[146:147], v[128:129], 0, v[146:147]
	v_lshlrev_b64 v[208:209], 11, v[122:123]
	v_lshl_add_u64 v[204:205], v[128:129], 0, v[204:205]
	v_lshl_add_u64 v[206:207], v[128:129], 0, v[206:207]
	v_lshl_add_u64 v[208:209], v[128:129], 0, v[208:209]
	v_or_b32_e32 v122, 4, v52
	s_lshl_b32 s8, s8, 1
	s_add_i32 s42, s42, s43
	s_add_i32 s44, s44, s45
	v_readlane_b32 s77, v247, 27
	v_readlane_b32 s78, v247, 28
	v_readlane_b32 s79, v247, 29
	v_readlane_b32 s80, v247, 30
	v_readlane_b32 s81, v247, 31
	v_readlane_b32 s82, v247, 32
	v_readlane_b32 s83, v247, 33
	v_readlane_b32 s90, v247, 40
	v_readlane_b32 s91, v247, 41
	s_waitcnt vmcnt(10)
	v_pk_fma_f32 v[180:181], v[32:33], v[180:181], v[44:45]
	v_pk_fma_f32 v[186:187], v[34:35], v[186:187], v[46:47]
	v_pk_fma_f32 v[210:211], v[32:33], v[182:183], v[44:45]
	v_pk_fma_f32 v[212:213], v[34:35], v[188:189], v[46:47]
	v_pk_fma_f32 v[214:215], v[32:33], v[184:185], v[44:45]
	v_pk_fma_f32 v[216:217], v[34:35], v[190:191], v[46:47]
	v_pk_fma_f32 v[218:219], v[32:33], v[192:193], v[44:45]
	v_pk_fma_f32 v[220:221], v[34:35], v[194:195], v[46:47]
	s_waitcnt vmcnt(9)
	v_pk_fma_f32 v[180:181], v[36:37], v[182:183], v[180:181]
	v_pk_fma_f32 v[182:183], v[38:39], v[188:189], v[186:187]
	v_pk_fma_f32 v[186:187], v[36:37], v[184:185], v[210:211]
	v_pk_fma_f32 v[188:189], v[38:39], v[190:191], v[212:213]
	v_pk_fma_f32 v[210:211], v[36:37], v[192:193], v[214:215]
	v_pk_fma_f32 v[212:213], v[38:39], v[194:195], v[216:217]
	v_pk_fma_f32 v[214:215], v[36:37], v[196:197], v[218:219]
	v_pk_fma_f32 v[216:217], v[38:39], v[198:199], v[220:221]
	s_waitcnt vmcnt(8)
	v_pk_fma_f32 v[180:181], v[40:41], v[184:185], v[180:181]
	v_pk_fma_f32 v[182:183], v[42:43], v[190:191], v[182:183]
	v_pk_fma_f32 v[184:185], v[40:41], v[192:193], v[186:187]
	v_pk_fma_f32 v[186:187], v[42:43], v[194:195], v[188:189]
	v_pk_fma_f32 v[188:189], v[40:41], v[196:197], v[210:211]
	v_pk_fma_f32 v[190:191], v[42:43], v[198:199], v[212:213]
	v_pk_fma_f32 v[192:193], v[40:41], v[200:201], v[214:215]
	v_pk_fma_f32 v[194:195], v[42:43], v[202:203], v[216:217]
	v_cvt_pk_bf16_f32 v180, v180, v181
	v_cvt_pk_bf16_f32 v181, v182, v183
	v_cvt_pk_bf16_f32 v182, v184, v185
	v_cvt_pk_bf16_f32 v183, v186, v187
	v_cvt_pk_bf16_f32 v184, v188, v189
	v_cvt_pk_bf16_f32 v185, v190, v191
	v_cvt_pk_bf16_f32 v186, v192, v193
	v_cvt_pk_bf16_f32 v187, v194, v195
	global_store_dwordx2 v[146:147], v[180:181], off nt
	global_store_dwordx2 v[204:205], v[182:183], off nt
	global_store_dwordx2 v[206:207], v[184:185], off nt
	global_store_dwordx2 v[208:209], v[186:187], off nt
	v_pk_fma_f32 v[180:181], v[32:33], v[196:197], v[44:45]
	v_pk_fma_f32 v[182:183], v[34:35], v[198:199], v[46:47]
	v_lshlrev_b32_e32 v146, 16, v154
	v_and_b32_e32 v147, 0xffff0000, v154
	v_pk_fma_f32 v[180:181], v[36:37], v[200:201], v[180:181]
	v_lshlrev_b32_e32 v154, 16, v155
	v_and_b32_e32 v155, 0xffff0000, v155
	v_pk_fma_f32 v[182:183], v[38:39], v[202:203], v[182:183]
	v_pk_fma_f32 v[180:181], v[40:41], v[146:147], v[180:181]
	v_pk_fma_f32 v[182:183], v[42:43], v[154:155], v[182:183]
	v_cvt_pk_bf16_f32 v180, v180, v181
	v_cvt_pk_bf16_f32 v181, v182, v183
	v_lshlrev_b64 v[182:183], 11, v[122:123]
	v_lshl_add_u64 v[182:183], v[128:129], 0, v[182:183]
	global_store_dwordx2 v[182:183], v[180:181], off nt
	v_pk_fma_f32 v[182:183], v[32:33], v[200:201], v[44:45]
	v_pk_fma_f32 v[184:185], v[34:35], v[202:203], v[46:47]
	v_lshlrev_b32_e32 v180, 16, v152
	v_and_b32_e32 v181, 0xffff0000, v152
	v_pk_fma_f32 v[182:183], v[36:37], v[146:147], v[182:183]
	v_lshlrev_b32_e32 v152, 16, v153
	v_and_b32_e32 v153, 0xffff0000, v153
	v_pk_fma_f32 v[184:185], v[38:39], v[154:155], v[184:185]
	v_pk_fma_f32 v[182:183], v[40:41], v[180:181], v[182:183]
	v_pk_fma_f32 v[184:185], v[42:43], v[152:153], v[184:185]
	v_or_b32_e32 v122, 5, v52
	v_cvt_pk_bf16_f32 v182, v182, v183
	v_cvt_pk_bf16_f32 v183, v184, v185
	v_lshlrev_b64 v[184:185], 11, v[122:123]
	v_lshl_add_u64 v[184:185], v[128:129], 0, v[184:185]
	v_pk_fma_f32 v[146:147], v[32:33], v[146:147], v[44:45]
	v_pk_fma_f32 v[154:155], v[34:35], v[154:155], v[46:47]
	global_store_dwordx2 v[184:185], v[182:183], off nt
	v_lshlrev_b32_e32 v182, 16, v148
	v_and_b32_e32 v183, 0xffff0000, v148
	v_pk_fma_f32 v[146:147], v[36:37], v[180:181], v[146:147]
	v_lshlrev_b32_e32 v148, 16, v149
	v_and_b32_e32 v149, 0xffff0000, v149
	v_pk_fma_f32 v[154:155], v[38:39], v[152:153], v[154:155]
	v_pk_fma_f32 v[146:147], v[40:41], v[182:183], v[146:147]
	v_pk_fma_f32 v[154:155], v[42:43], v[148:149], v[154:155]
	v_or_b32_e32 v122, 6, v52
	v_cvt_pk_bf16_f32 v146, v146, v147
	v_cvt_pk_bf16_f32 v147, v154, v155
	v_lshlrev_b64 v[154:155], 11, v[122:123]
	v_lshl_add_u64 v[154:155], v[128:129], 0, v[154:155]
	global_store_dwordx2 v[154:155], v[146:147], off nt
	v_pk_fma_f32 v[154:155], v[32:33], v[180:181], v[44:45]
	v_pk_fma_f32 v[152:153], v[34:35], v[152:153], v[46:47]
	v_lshlrev_b32_e32 v146, 16, v150
	v_and_b32_e32 v147, 0xffff0000, v150
	v_pk_fma_f32 v[154:155], v[36:37], v[182:183], v[154:155]
	v_lshlrev_b32_e32 v150, 16, v151
	v_and_b32_e32 v151, 0xffff0000, v151
	v_pk_fma_f32 v[152:153], v[38:39], v[148:149], v[152:153]
	v_pk_fma_f32 v[154:155], v[40:41], v[146:147], v[154:155]
	v_pk_fma_f32 v[152:153], v[42:43], v[150:151], v[152:153]
	v_or_b32_e32 v122, 7, v52
	v_cvt_pk_bf16_f32 v154, v154, v155
	v_cvt_pk_bf16_f32 v155, v152, v153
	v_lshlrev_b64 v[152:153], 11, v[122:123]
	v_lshl_add_u64 v[152:153], v[128:129], 0, v[152:153]
	global_store_dwordx2 v[152:153], v[154:155], off nt
	v_pk_fma_f32 v[154:155], v[32:33], v[182:183], v[44:45]
	v_pk_fma_f32 v[148:149], v[34:35], v[148:149], v[46:47]
	v_lshlrev_b32_e32 v152, 16, v144
	v_and_b32_e32 v153, 0xffff0000, v144
	v_pk_fma_f32 v[154:155], v[36:37], v[146:147], v[154:155]
	v_lshlrev_b32_e32 v144, 16, v145
	v_and_b32_e32 v145, 0xffff0000, v145
	v_pk_fma_f32 v[148:149], v[38:39], v[150:151], v[148:149]
	v_pk_fma_f32 v[154:155], v[40:41], v[152:153], v[154:155]
	v_pk_fma_f32 v[148:149], v[42:43], v[144:145], v[148:149]
	v_or_b32_e32 v122, 8, v52
	v_cvt_pk_bf16_f32 v154, v154, v155
	v_cvt_pk_bf16_f32 v155, v148, v149
	v_lshlrev_b64 v[148:149], 11, v[122:123]
	v_lshl_add_u64 v[148:149], v[128:129], 0, v[148:149]
	v_pk_fma_f32 v[146:147], v[32:33], v[146:147], v[44:45]
	v_pk_fma_f32 v[150:151], v[34:35], v[150:151], v[46:47]
	global_store_dwordx2 v[148:149], v[154:155], off nt
	v_lshlrev_b32_e32 v148, 16, v142
	v_and_b32_e32 v149, 0xffff0000, v142
	v_pk_fma_f32 v[146:147], v[36:37], v[152:153], v[146:147]
	v_lshlrev_b32_e32 v142, 16, v143
	v_and_b32_e32 v143, 0xffff0000, v143
	v_pk_fma_f32 v[150:151], v[38:39], v[144:145], v[150:151]
	v_pk_fma_f32 v[146:147], v[40:41], v[148:149], v[146:147]
	v_pk_fma_f32 v[150:151], v[42:43], v[142:143], v[150:151]
	v_or_b32_e32 v122, 9, v52
	v_cvt_pk_bf16_f32 v146, v146, v147
	v_cvt_pk_bf16_f32 v147, v150, v151
	v_lshlrev_b64 v[150:151], 11, v[122:123]
	v_lshl_add_u64 v[150:151], v[128:129], 0, v[150:151]
	global_store_dwordx2 v[150:151], v[146:147], off nt
	v_pk_fma_f32 v[150:151], v[32:33], v[152:153], v[44:45]
	v_pk_fma_f32 v[144:145], v[34:35], v[144:145], v[46:47]
	v_lshlrev_b32_e32 v146, 16, v138
	v_and_b32_e32 v147, 0xffff0000, v138
	v_pk_fma_f32 v[150:151], v[36:37], v[148:149], v[150:151]
	v_lshlrev_b32_e32 v138, 16, v139
	v_and_b32_e32 v139, 0xffff0000, v139
	v_pk_fma_f32 v[144:145], v[38:39], v[142:143], v[144:145]
	v_pk_fma_f32 v[150:151], v[40:41], v[146:147], v[150:151]
	v_pk_fma_f32 v[144:145], v[42:43], v[138:139], v[144:145]
	v_or_b32_e32 v122, 10, v52
	v_cvt_pk_bf16_f32 v150, v150, v151
	v_cvt_pk_bf16_f32 v151, v144, v145
	v_lshlrev_b64 v[144:145], 11, v[122:123]
	v_lshl_add_u64 v[144:145], v[128:129], 0, v[144:145]
	v_pk_fma_f32 v[148:149], v[32:33], v[148:149], v[44:45]
	v_pk_fma_f32 v[142:143], v[34:35], v[142:143], v[46:47]
	global_store_dwordx2 v[144:145], v[150:151], off nt
	v_lshlrev_b32_e32 v144, 16, v140
	v_and_b32_e32 v145, 0xffff0000, v140
	v_pk_fma_f32 v[148:149], v[36:37], v[146:147], v[148:149]
	v_lshlrev_b32_e32 v140, 16, v141
	v_and_b32_e32 v141, 0xffff0000, v141
	v_pk_fma_f32 v[142:143], v[38:39], v[138:139], v[142:143]
	v_pk_fma_f32 v[148:149], v[40:41], v[144:145], v[148:149]
	v_pk_fma_f32 v[142:143], v[42:43], v[140:141], v[142:143]
	v_or_b32_e32 v122, 11, v52
	v_cvt_pk_bf16_f32 v148, v148, v149
	v_cvt_pk_bf16_f32 v149, v142, v143
	v_lshlrev_b64 v[142:143], 11, v[122:123]
	v_lshl_add_u64 v[142:143], v[128:129], 0, v[142:143]
	v_pk_fma_f32 v[146:147], v[32:33], v[146:147], v[44:45]
	v_pk_fma_f32 v[138:139], v[34:35], v[138:139], v[46:47]
	global_store_dwordx2 v[142:143], v[148:149], off nt
	v_lshlrev_b32_e32 v142, 16, v136
	v_and_b32_e32 v143, 0xffff0000, v136
	v_pk_fma_f32 v[146:147], v[36:37], v[144:145], v[146:147]
	v_lshlrev_b32_e32 v136, 16, v137
	v_and_b32_e32 v137, 0xffff0000, v137
	v_pk_fma_f32 v[138:139], v[38:39], v[140:141], v[138:139]
	v_pk_fma_f32 v[146:147], v[40:41], v[142:143], v[146:147]
	v_pk_fma_f32 v[138:139], v[42:43], v[136:137], v[138:139]
	v_or_b32_e32 v122, 12, v52
	v_cvt_pk_bf16_f32 v146, v146, v147
	v_cvt_pk_bf16_f32 v147, v138, v139
	v_lshlrev_b64 v[138:139], 11, v[122:123]
	v_lshl_add_u64 v[138:139], v[128:129], 0, v[138:139]
	v_pk_fma_f32 v[144:145], v[32:33], v[144:145], v[44:45]
	v_pk_fma_f32 v[140:141], v[34:35], v[140:141], v[46:47]
	global_store_dwordx2 v[138:139], v[146:147], off nt
	v_lshlrev_b32_e32 v138, 16, v134
	v_and_b32_e32 v139, 0xffff0000, v134
	v_pk_fma_f32 v[144:145], v[36:37], v[142:143], v[144:145]
	v_lshlrev_b32_e32 v134, 16, v135
	v_and_b32_e32 v135, 0xffff0000, v135
	v_pk_fma_f32 v[140:141], v[38:39], v[136:137], v[140:141]
	v_pk_fma_f32 v[144:145], v[40:41], v[138:139], v[144:145]
	v_pk_fma_f32 v[140:141], v[42:43], v[134:135], v[140:141]
	v_or_b32_e32 v122, 13, v52
	v_cvt_pk_bf16_f32 v144, v144, v145
	v_cvt_pk_bf16_f32 v145, v140, v141
	v_lshlrev_b64 v[140:141], 11, v[122:123]
	v_lshl_add_u64 v[140:141], v[128:129], 0, v[140:141]
	v_pk_fma_f32 v[142:143], v[32:33], v[142:143], v[44:45]
	v_pk_fma_f32 v[136:137], v[34:35], v[136:137], v[46:47]
	global_store_dwordx2 v[140:141], v[144:145], off nt
	v_lshlrev_b32_e32 v140, 16, v132
	v_and_b32_e32 v141, 0xffff0000, v132
	v_pk_fma_f32 v[142:143], v[36:37], v[138:139], v[142:143]
	v_lshlrev_b32_e32 v132, 16, v133
	v_and_b32_e32 v133, 0xffff0000, v133
	v_pk_fma_f32 v[136:137], v[38:39], v[134:135], v[136:137]
	v_pk_fma_f32 v[32:33], v[32:33], v[138:139], v[44:45]
	v_pk_fma_f32 v[34:35], v[34:35], v[134:135], v[46:47]
	v_pk_fma_f32 v[142:143], v[40:41], v[140:141], v[142:143]
	v_pk_fma_f32 v[136:137], v[42:43], v[132:133], v[136:137]
	v_or_b32_e32 v122, 14, v52
	v_pk_fma_f32 v[32:33], v[36:37], v[140:141], v[32:33]
	v_lshlrev_b32_e32 v36, 16, v131
	v_and_b32_e32 v37, 0xffff0000, v131
	v_pk_fma_f32 v[34:35], v[38:39], v[132:133], v[34:35]
	v_cvt_pk_bf16_f32 v142, v142, v143
	v_cvt_pk_bf16_f32 v143, v136, v137
	v_lshlrev_b64 v[136:137], 11, v[122:123]
	v_pk_fma_f32 v[34:35], v[42:43], v[36:37], v[34:35]
	v_lshlrev_b32_e32 v39, 16, v66
	v_lshlrev_b32_e32 v38, 16, v64
	v_lshlrev_b32_e32 v155, 16, v68
	v_lshlrev_b32_e32 v154, 16, v62
	v_lshlrev_b32_e32 v37, 16, v60
	v_lshlrev_b32_e32 v36, 16, v54
	v_lshlrev_b32_e32 v181, 16, v58
	v_lshlrev_b32_e32 v180, 16, v56
	v_lshl_add_u64 v[136:137], v[128:129], 0, v[136:137]
	s_waitcnt vmcnt(15)
	v_pk_fma_f32 v[182:183], v[20:21], v[36:37], v[28:29] op_sel_hi:[0,1,0]
	s_waitcnt vmcnt(14)
	v_pk_fma_f32 v[184:185], v[16:17], v[180:181], v[24:25] op_sel_hi:[0,1,0]
	v_pk_mov_b32 v[36:37], v[36:37], v[38:39] op_sel:[1,0]
	v_pk_mov_b32 v[180:181], v[180:181], v[154:155] op_sel:[1,0]
	global_store_dwordx2 v[136:137], v[142:143], off nt
	v_lshlrev_b32_e32 v136, 16, v130
	v_and_b32_e32 v137, 0xffff0000, v130
	v_pk_fma_f32 v[36:37], v[12:13], v[36:37], v[182:183] op_sel_hi:[0,1,1]
	v_pk_fma_f32 v[180:181], v[0:1], v[180:181], v[184:185] op_sel_hi:[0,1,1]
	v_pk_fma_f32 v[32:33], v[40:41], v[136:137], v[32:33]
	v_lshlrev_b32_e32 v41, 16, v76
	v_lshlrev_b32_e32 v40, 16, v72
	v_lshlrev_b32_e32 v153, 16, v74
	v_lshlrev_b32_e32 v152, 16, v70
	v_pk_fma_f32 v[36:37], v[8:9], v[38:39], v[36:37] op_sel_hi:[0,1,1]
	v_pk_fma_f32 v[180:181], v[4:5], v[154:155], v[180:181] op_sel_hi:[0,1,1]
	v_pk_mul_f32 v[36:37], v[36:37], v[180:181]
	v_pk_fma_f32 v[180:181], v[20:21], v[38:39], v[28:29] op_sel_hi:[0,1,0]
	v_pk_fma_f32 v[182:183], v[16:17], v[154:155], v[24:25] op_sel_hi:[0,1,0]
	v_pk_mov_b32 v[38:39], v[38:39], v[40:41] op_sel:[1,0]
	v_pk_mov_b32 v[154:155], v[154:155], v[152:153] op_sel:[1,0]
	v_pk_fma_f32 v[38:39], v[12:13], v[38:39], v[180:181] op_sel_hi:[0,1,1]
	v_pk_fma_f32 v[154:155], v[0:1], v[154:155], v[182:183] op_sel_hi:[0,1,1]
	v_lshlrev_b32_e32 v43, 16, v82
	v_lshlrev_b32_e32 v42, 16, v80
	v_lshlrev_b32_e32 v151, 16, v84
	v_lshlrev_b32_e32 v150, 16, v78
	v_pk_fma_f32 v[38:39], v[8:9], v[40:41], v[38:39] op_sel_hi:[0,1,1]
	v_pk_fma_f32 v[154:155], v[4:5], v[152:153], v[154:155] op_sel_hi:[0,1,1]
	v_pk_mul_f32 v[38:39], v[38:39], v[154:155]
	v_pk_fma_f32 v[154:155], v[20:21], v[40:41], v[28:29] op_sel_hi:[0,1,0]
	v_pk_fma_f32 v[180:181], v[16:17], v[152:153], v[24:25] op_sel_hi:[0,1,0]
	v_pk_mov_b32 v[40:41], v[40:41], v[42:43] op_sel:[1,0]
	v_pk_mov_b32 v[152:153], v[152:153], v[150:151] op_sel:[1,0]
	v_pk_fma_f32 v[40:41], v[12:13], v[40:41], v[154:155] op_sel_hi:[0,1,1]
	v_pk_fma_f32 v[152:153], v[0:1], v[152:153], v[180:181] op_sel_hi:[0,1,1]
	v_lshlrev_b32_e32 v45, 16, v92
	v_lshlrev_b32_e32 v44, 16, v88
	v_lshlrev_b32_e32 v149, 16, v90
	v_lshlrev_b32_e32 v148, 16, v86
	v_pk_fma_f32 v[40:41], v[8:9], v[42:43], v[40:41] op_sel_hi:[0,1,1]
	v_pk_fma_f32 v[152:153], v[4:5], v[150:151], v[152:153] op_sel_hi:[0,1,1]
	v_pk_mul_f32 v[40:41], v[40:41], v[152:153]
	v_pk_fma_f32 v[152:153], v[20:21], v[42:43], v[28:29] op_sel_hi:[0,1,0]
	v_pk_fma_f32 v[154:155], v[16:17], v[150:151], v[24:25] op_sel_hi:[0,1,0]
	v_pk_mov_b32 v[42:43], v[42:43], v[44:45] op_sel:[1,0]
	v_pk_mov_b32 v[150:151], v[150:151], v[148:149] op_sel:[1,0]
	v_pk_fma_f32 v[42:43], v[12:13], v[42:43], v[152:153] op_sel_hi:[0,1,1]
	v_pk_fma_f32 v[150:151], v[0:1], v[150:151], v[154:155] op_sel_hi:[0,1,1]
	v_lshlrev_b32_e32 v47, 16, v98
	v_lshlrev_b32_e32 v46, 16, v96
	v_lshlrev_b32_e32 v147, 16, v100
	v_lshlrev_b32_e32 v146, 16, v94
	v_pk_fma_f32 v[42:43], v[8:9], v[44:45], v[42:43] op_sel_hi:[0,1,1]
	v_pk_fma_f32 v[150:151], v[4:5], v[148:149], v[150:151] op_sel_hi:[0,1,1]
	v_pk_mul_f32 v[42:43], v[42:43], v[150:151]
	v_pk_fma_f32 v[150:151], v[20:21], v[44:45], v[28:29] op_sel_hi:[0,1,0]
	v_pk_fma_f32 v[152:153], v[16:17], v[148:149], v[24:25] op_sel_hi:[0,1,0]
	v_pk_mov_b32 v[44:45], v[44:45], v[46:47] op_sel:[1,0]
	v_pk_mov_b32 v[148:149], v[148:149], v[146:147] op_sel:[1,0]
	v_pk_fma_f32 v[44:45], v[12:13], v[44:45], v[150:151] op_sel_hi:[0,1,1]
	v_pk_fma_f32 v[148:149], v[0:1], v[148:149], v[152:153] op_sel_hi:[0,1,1]
	v_lshlrev_b32_e32 v131, 16, v108
	v_lshlrev_b32_e32 v130, 16, v104
	v_lshlrev_b32_e32 v145, 16, v106
	v_lshlrev_b32_e32 v144, 16, v102
	v_pk_fma_f32 v[44:45], v[8:9], v[46:47], v[44:45] op_sel_hi:[0,1,1]
	v_pk_fma_f32 v[148:149], v[4:5], v[146:147], v[148:149] op_sel_hi:[0,1,1]
	v_pk_mul_f32 v[44:45], v[44:45], v[148:149]
	v_pk_fma_f32 v[148:149], v[20:21], v[46:47], v[28:29] op_sel_hi:[0,1,0]
	v_pk_fma_f32 v[150:151], v[16:17], v[146:147], v[24:25] op_sel_hi:[0,1,0]
	v_pk_mov_b32 v[46:47], v[46:47], v[130:131] op_sel:[1,0]
	v_pk_mov_b32 v[146:147], v[146:147], v[144:145] op_sel:[1,0]
	v_pk_fma_f32 v[46:47], v[12:13], v[46:47], v[148:149] op_sel_hi:[0,1,1]
	v_pk_fma_f32 v[146:147], v[0:1], v[146:147], v[150:151] op_sel_hi:[0,1,1]
	v_lshlrev_b32_e32 v132, 16, v112
	v_lshlrev_b32_e32 v133, 16, v114
	v_lshlrev_b32_e32 v134, 16, v110
	v_lshlrev_b32_e32 v135, 16, v118
	v_pk_fma_f32 v[46:47], v[8:9], v[130:131], v[46:47] op_sel_hi:[0,1,1]
	v_pk_fma_f32 v[146:147], v[4:5], v[144:145], v[146:147] op_sel_hi:[0,1,1]
	v_pk_mul_f32 v[46:47], v[46:47], v[146:147]
	v_pk_fma_f32 v[146:147], v[20:21], v[130:131], v[28:29] op_sel_hi:[0,1,0]
	v_pk_fma_f32 v[148:149], v[16:17], v[144:145], v[24:25] op_sel_hi:[0,1,0]
	v_pk_mov_b32 v[130:131], v[130:131], v[132:133] op_sel:[1,0]
	v_pk_mov_b32 v[144:145], v[144:145], v[134:135] op_sel:[1,0]
	v_pk_fma_f32 v[130:131], v[12:13], v[130:131], v[146:147] op_sel_hi:[0,1,1]
	v_pk_fma_f32 v[144:145], v[0:1], v[144:145], v[148:149] op_sel_hi:[0,1,1]
	v_lshlrev_b32_e32 v139, 16, v120
	v_mov_b32_e32 v138, v133
	v_lshlrev_b32_e32 v143, 16, v116
	v_mov_b32_e32 v142, v135
	v_pk_fma_f32 v[130:131], v[8:9], v[132:133], v[130:131] op_sel_hi:[0,1,1]
	v_pk_fma_f32 v[144:145], v[4:5], v[134:135], v[144:145] op_sel_hi:[0,1,1]
	v_pk_fma_f32 v[132:133], v[20:21], v[132:133], v[28:29] op_sel_hi:[0,1,0]
	v_pk_fma_f32 v[134:135], v[16:17], v[134:135], v[24:25] op_sel_hi:[0,1,0]
	v_lshlrev_b32_e32 v137, 16, v124
	v_lshlrev_b32_e32 v141, 16, v126
	v_mov_b32_e32 v136, v139
	v_pk_fma_f32 v[132:133], v[12:13], v[138:139], v[132:133] op_sel_hi:[0,1,1]
	v_mov_b32_e32 v140, v143
	v_pk_fma_f32 v[134:135], v[0:1], v[142:143], v[134:135] op_sel_hi:[0,1,1]
	v_pk_fma_f32 v[132:133], v[8:9], v[136:137], v[132:133] op_sel_hi:[0,1,1]
	v_pk_fma_f32 v[134:135], v[4:5], v[140:141], v[134:135] op_sel_hi:[0,1,1]
	v_pk_mul_f32 v[132:133], v[132:133], v[134:135]
	v_and_b32_e32 v137, 0xffff0000, v66
	v_and_b32_e32 v136, 0xffff0000, v64
	v_and_b32_e32 v195, 0xffff0000, v68
	v_and_b32_e32 v194, 0xffff0000, v62
	v_and_b32_e32 v135, 0xffff0000, v60
	v_and_b32_e32 v134, 0xffff0000, v54
	v_and_b32_e32 v197, 0xffff0000, v58
	v_and_b32_e32 v196, 0xffff0000, v56
	v_pk_fma_f32 v[198:199], v[20:21], v[134:135], v[28:29] op_sel:[1,0,1]
	v_pk_fma_f32 v[200:201], v[16:17], v[196:197], v[24:25] op_sel:[1,0,1]
	v_pk_mov_b32 v[134:135], v[134:135], v[136:137] op_sel:[1,0]
	v_pk_mov_b32 v[196:197], v[196:197], v[194:195] op_sel:[1,0]
	v_pk_fma_f32 v[134:135], v[12:13], v[134:135], v[198:199] op_sel:[1,0,0]
	v_pk_fma_f32 v[196:197], v[0:1], v[196:197], v[200:201] op_sel:[1,0,0]
	v_and_b32_e32 v139, 0xffff0000, v76
	v_and_b32_e32 v138, 0xffff0000, v72
	v_and_b32_e32 v193, 0xffff0000, v74
	v_and_b32_e32 v192, 0xffff0000, v70
	v_pk_fma_f32 v[134:135], v[8:9], v[136:137], v[134:135] op_sel:[1,0,0]
	v_pk_fma_f32 v[196:197], v[4:5], v[194:195], v[196:197] op_sel:[1,0,0]
	v_pk_fma_f32 v[198:199], v[16:17], v[194:195], v[24:25] op_sel:[1,0,1]
	v_pk_mul_f32 v[134:135], v[134:135], v[196:197]
	v_pk_fma_f32 v[196:197], v[20:21], v[136:137], v[28:29] op_sel:[1,0,1]
	v_pk_mov_b32 v[136:137], v[136:137], v[138:139] op_sel:[1,0]
	v_pk_mov_b32 v[194:195], v[194:195], v[192:193] op_sel:[1,0]
	v_pk_fma_f32 v[136:137], v[12:13], v[136:137], v[196:197] op_sel:[1,0,0]
	v_pk_fma_f32 v[194:195], v[0:1], v[194:195], v[198:199] op_sel:[1,0,0]
	v_and_b32_e32 v141, 0xffff0000, v82
	v_and_b32_e32 v140, 0xffff0000, v80
	v_and_b32_e32 v191, 0xffff0000, v84
	v_and_b32_e32 v190, 0xffff0000, v78
	v_pk_fma_f32 v[136:137], v[8:9], v[138:139], v[136:137] op_sel:[1,0,0]
	v_pk_fma_f32 v[194:195], v[4:5], v[192:193], v[194:195] op_sel:[1,0,0]
	v_pk_fma_f32 v[196:197], v[16:17], v[192:193], v[24:25] op_sel:[1,0,1]
	v_pk_mul_f32 v[136:137], v[136:137], v[194:195]
	v_pk_fma_f32 v[194:195], v[20:21], v[138:139], v[28:29] op_sel:[1,0,1]
	v_pk_mov_b32 v[138:139], v[138:139], v[140:141] op_sel:[1,0]
	v_pk_mov_b32 v[192:193], v[192:193], v[190:191] op_sel:[1,0]
	v_pk_fma_f32 v[138:139], v[12:13], v[138:139], v[194:195] op_sel:[1,0,0]
	v_pk_fma_f32 v[192:193], v[0:1], v[192:193], v[196:197] op_sel:[1,0,0]
	v_and_b32_e32 v143, 0xffff0000, v92
	v_and_b32_e32 v142, 0xffff0000, v88
	v_and_b32_e32 v189, 0xffff0000, v90
	v_and_b32_e32 v188, 0xffff0000, v86
	v_pk_fma_f32 v[138:139], v[8:9], v[140:141], v[138:139] op_sel:[1,0,0]
	v_pk_fma_f32 v[192:193], v[4:5], v[190:191], v[192:193] op_sel:[1,0,0]
	v_pk_fma_f32 v[194:195], v[16:17], v[190:191], v[24:25] op_sel:[1,0,1]
	v_pk_mul_f32 v[138:139], v[138:139], v[192:193]
	v_pk_fma_f32 v[192:193], v[20:21], v[140:141], v[28:29] op_sel:[1,0,1]
	v_pk_mov_b32 v[140:141], v[140:141], v[142:143] op_sel:[1,0]
	v_pk_mov_b32 v[190:191], v[190:191], v[188:189] op_sel:[1,0]
	v_pk_fma_f32 v[140:141], v[12:13], v[140:141], v[192:193] op_sel:[1,0,0]
	v_pk_fma_f32 v[190:191], v[0:1], v[190:191], v[194:195] op_sel:[1,0,0]
	v_pk_mul_f32 v[130:131], v[130:131], v[144:145]
	v_and_b32_e32 v145, 0xffff0000, v98
	v_and_b32_e32 v144, 0xffff0000, v96
	v_and_b32_e32 v187, 0xffff0000, v100
	v_and_b32_e32 v186, 0xffff0000, v94
	v_pk_fma_f32 v[140:141], v[8:9], v[142:143], v[140:141] op_sel:[1,0,0]
	v_pk_fma_f32 v[190:191], v[4:5], v[188:189], v[190:191] op_sel:[1,0,0]
	v_pk_fma_f32 v[192:193], v[16:17], v[188:189], v[24:25] op_sel:[1,0,1]
	v_pk_mul_f32 v[140:141], v[140:141], v[190:191]
	v_pk_fma_f32 v[190:191], v[20:21], v[142:143], v[28:29] op_sel:[1,0,1]
	v_pk_mov_b32 v[142:143], v[142:143], v[144:145] op_sel:[1,0]
	v_pk_mov_b32 v[188:189], v[188:189], v[186:187] op_sel:[1,0]
	v_pk_fma_f32 v[142:143], v[12:13], v[142:143], v[190:191] op_sel:[1,0,0]
	v_pk_fma_f32 v[188:189], v[0:1], v[188:189], v[192:193] op_sel:[1,0,0]
	v_and_b32_e32 v147, 0xffff0000, v108
	v_and_b32_e32 v146, 0xffff0000, v104
	v_and_b32_e32 v185, 0xffff0000, v106
	v_and_b32_e32 v184, 0xffff0000, v102
	v_pk_fma_f32 v[142:143], v[8:9], v[144:145], v[142:143] op_sel:[1,0,0]
	v_pk_fma_f32 v[188:189], v[4:5], v[186:187], v[188:189] op_sel:[1,0,0]
	v_pk_fma_f32 v[190:191], v[16:17], v[186:187], v[24:25] op_sel:[1,0,1]
	v_pk_mul_f32 v[142:143], v[142:143], v[188:189]
	v_pk_fma_f32 v[188:189], v[20:21], v[144:145], v[28:29] op_sel:[1,0,1]
	v_pk_mov_b32 v[144:145], v[144:145], v[146:147] op_sel:[1,0]
	v_pk_mov_b32 v[186:187], v[186:187], v[184:185] op_sel:[1,0]
	v_pk_fma_f32 v[144:145], v[12:13], v[144:145], v[188:189] op_sel:[1,0,0]
	v_pk_fma_f32 v[186:187], v[0:1], v[186:187], v[190:191] op_sel:[1,0,0]
	v_and_b32_e32 v149, 0xffff0000, v114
	v_and_b32_e32 v148, 0xffff0000, v112
	v_pk_fma_f32 v[144:145], v[8:9], v[146:147], v[144:145] op_sel:[1,0,0]
	v_pk_fma_f32 v[186:187], v[4:5], v[184:185], v[186:187] op_sel:[1,0,0]
	v_and_b32_e32 v151, 0xffff0000, v120
	v_mov_b32_e32 v150, v149
	v_pk_mul_f32 v[144:145], v[144:145], v[186:187]
	v_pk_fma_f32 v[186:187], v[20:21], v[146:147], v[28:29] op_sel:[1,0,1]
	v_pk_mov_b32 v[146:147], v[146:147], v[148:149] op_sel:[1,0]
	v_pk_fma_f32 v[20:21], v[20:21], v[148:149], v[28:29] op_sel:[1,0,1]
	v_and_b32_e32 v153, 0xffff0000, v118
	v_and_b32_e32 v152, 0xffff0000, v110
	v_and_b32_e32 v181, 0xffff0000, v124
	v_mov_b32_e32 v180, v151
	v_pk_fma_f32 v[146:147], v[12:13], v[146:147], v[186:187] op_sel:[1,0,0]
	v_pk_fma_f32 v[12:13], v[12:13], v[150:151], v[20:21] op_sel:[1,0,0]
	v_and_b32_e32 v155, 0xffff0000, v116
	v_mov_b32_e32 v154, v153
	v_pk_fma_f32 v[188:189], v[16:17], v[184:185], v[24:25] op_sel:[1,0,1]
	v_pk_fma_f32 v[146:147], v[8:9], v[148:149], v[146:147] op_sel:[1,0,0]
	v_pk_mov_b32 v[184:185], v[184:185], v[152:153] op_sel:[1,0]
	v_pk_fma_f32 v[8:9], v[8:9], v[180:181], v[12:13] op_sel:[1,0,0]
	v_pk_fma_f32 v[12:13], v[16:17], v[152:153], v[24:25] op_sel:[1,0,1]
	v_and_b32_e32 v183, 0xffff0000, v126
	v_mov_b32_e32 v182, v155
	v_pk_fma_f32 v[184:185], v[0:1], v[184:185], v[188:189] op_sel:[1,0,0]
	v_pk_fma_f32 v[0:1], v[0:1], v[154:155], v[12:13] op_sel:[1,0,0]
	v_pk_fma_f32 v[184:185], v[4:5], v[152:153], v[184:185] op_sel:[1,0,0]
	v_pk_fma_f32 v[0:1], v[4:5], v[182:183], v[0:1] op_sel:[1,0,0]
	v_lshlrev_b32_e32 v195, 16, v69
	v_pk_mul_f32 v[0:1], v[8:9], v[0:1]
	v_lshlrev_b32_e32 v9, 16, v67
	v_lshlrev_b32_e32 v8, 16, v65
	v_lshlrev_b32_e32 v194, 16, v63
	v_lshlrev_b32_e32 v5, 16, v61
	v_lshlrev_b32_e32 v4, 16, v55
	v_lshlrev_b32_e32 v197, 16, v59
	v_lshlrev_b32_e32 v196, 16, v57
	v_pk_fma_f32 v[198:199], v[22:23], v[4:5], v[30:31] op_sel_hi:[0,1,0]
	v_pk_fma_f32 v[200:201], v[18:19], v[196:197], v[26:27] op_sel_hi:[0,1,0]
	v_pk_mov_b32 v[4:5], v[4:5], v[8:9] op_sel:[1,0]
	v_pk_mov_b32 v[196:197], v[196:197], v[194:195] op_sel:[1,0]
	v_pk_fma_f32 v[4:5], v[14:15], v[4:5], v[198:199] op_sel_hi:[0,1,1]
	v_pk_fma_f32 v[196:197], v[2:3], v[196:197], v[200:201] op_sel_hi:[0,1,1]
	v_lshlrev_b32_e32 v191, 16, v77
	v_lshlrev_b32_e32 v190, 16, v73
	v_lshlrev_b32_e32 v193, 16, v75
	v_lshlrev_b32_e32 v192, 16, v71
	v_pk_fma_f32 v[4:5], v[10:11], v[8:9], v[4:5] op_sel_hi:[0,1,1]
	v_pk_fma_f32 v[196:197], v[6:7], v[194:195], v[196:197] op_sel_hi:[0,1,1]
	v_pk_mul_f32 v[4:5], v[4:5], v[196:197]
	v_pk_fma_f32 v[196:197], v[22:23], v[8:9], v[30:31] op_sel_hi:[0,1,0]
	v_pk_fma_f32 v[198:199], v[18:19], v[194:195], v[26:27] op_sel_hi:[0,1,0]
	v_pk_mov_b32 v[8:9], v[8:9], v[190:191] op_sel:[1,0]
	v_pk_mov_b32 v[194:195], v[194:195], v[192:193] op_sel:[1,0]
	v_pk_fma_f32 v[8:9], v[14:15], v[8:9], v[196:197] op_sel_hi:[0,1,1]
	v_pk_fma_f32 v[194:195], v[2:3], v[194:195], v[198:199] op_sel_hi:[0,1,1]
	v_lshlrev_b32_e32 v187, 16, v83
	v_lshlrev_b32_e32 v186, 16, v81
	v_lshlrev_b32_e32 v189, 16, v85
	v_lshlrev_b32_e32 v188, 16, v79
	v_pk_fma_f32 v[8:9], v[10:11], v[190:191], v[8:9] op_sel_hi:[0,1,1]
	v_pk_fma_f32 v[194:195], v[6:7], v[192:193], v[194:195] op_sel_hi:[0,1,1]
	v_pk_mul_f32 v[8:9], v[8:9], v[194:195]
	v_pk_fma_f32 v[194:195], v[22:23], v[190:191], v[30:31] op_sel_hi:[0,1,0]
	v_pk_fma_f32 v[196:197], v[18:19], v[192:193], v[26:27] op_sel_hi:[0,1,0]
	v_pk_mov_b32 v[190:191], v[190:191], v[186:187] op_sel:[1,0]
	v_pk_mov_b32 v[192:193], v[192:193], v[188:189] op_sel:[1,0]
	v_pk_fma_f32 v[190:191], v[14:15], v[190:191], v[194:195] op_sel_hi:[0,1,1]
	v_pk_fma_f32 v[192:193], v[2:3], v[192:193], v[196:197] op_sel_hi:[0,1,1]
	v_pk_mul_f32 v[146:147], v[146:147], v[184:185]
	v_lshlrev_b32_e32 v183, 16, v93
	v_lshlrev_b32_e32 v182, 16, v89
	v_lshlrev_b32_e32 v185, 16, v91
	v_lshlrev_b32_e32 v184, 16, v87
	v_pk_fma_f32 v[190:191], v[10:11], v[186:187], v[190:191] op_sel_hi:[0,1,1]
	v_pk_fma_f32 v[192:193], v[6:7], v[188:189], v[192:193] op_sel_hi:[0,1,1]
	v_pk_mul_f32 v[190:191], v[190:191], v[192:193]
	v_pk_fma_f32 v[192:193], v[22:23], v[186:187], v[30:31] op_sel_hi:[0,1,0]
	v_pk_fma_f32 v[194:195], v[18:19], v[188:189], v[26:27] op_sel_hi:[0,1,0]
	v_pk_mov_b32 v[186:187], v[186:187], v[182:183] op_sel:[1,0]
	v_pk_mov_b32 v[188:189], v[188:189], v[184:185] op_sel:[1,0]
	v_pk_fma_f32 v[186:187], v[14:15], v[186:187], v[192:193] op_sel_hi:[0,1,1]
	v_pk_fma_f32 v[188:189], v[2:3], v[188:189], v[194:195] op_sel_hi:[0,1,1]
	v_lshlrev_b32_e32 v155, 16, v99
	v_lshlrev_b32_e32 v154, 16, v97
	v_lshlrev_b32_e32 v181, 16, v101
	v_lshlrev_b32_e32 v180, 16, v95
	v_pk_fma_f32 v[186:187], v[10:11], v[182:183], v[186:187] op_sel_hi:[0,1,1]
	v_pk_fma_f32 v[188:189], v[6:7], v[184:185], v[188:189] op_sel_hi:[0,1,1]
	v_pk_mul_f32 v[186:187], v[186:187], v[188:189]
	v_pk_fma_f32 v[188:189], v[22:23], v[182:183], v[30:31] op_sel_hi:[0,1,0]
	v_pk_fma_f32 v[192:193], v[18:19], v[184:185], v[26:27] op_sel_hi:[0,1,0]
	v_pk_mov_b32 v[182:183], v[182:183], v[154:155] op_sel:[1,0]
	v_pk_mov_b32 v[184:185], v[184:185], v[180:181] op_sel:[1,0]
	v_pk_fma_f32 v[182:183], v[14:15], v[182:183], v[188:189] op_sel_hi:[0,1,1]
	v_pk_fma_f32 v[184:185], v[2:3], v[184:185], v[192:193] op_sel_hi:[0,1,1]
	v_lshlrev_b32_e32 v151, 16, v109
	v_lshlrev_b32_e32 v150, 16, v105
	v_lshlrev_b32_e32 v153, 16, v107
	v_lshlrev_b32_e32 v152, 16, v103
	v_pk_fma_f32 v[182:183], v[10:11], v[154:155], v[182:183] op_sel_hi:[0,1,1]
	v_pk_fma_f32 v[184:185], v[6:7], v[180:181], v[184:185] op_sel_hi:[0,1,1]
	v_pk_mul_f32 v[182:183], v[182:183], v[184:185]
	v_pk_fma_f32 v[184:185], v[22:23], v[154:155], v[30:31] op_sel_hi:[0,1,0]
	v_pk_fma_f32 v[188:189], v[18:19], v[180:181], v[26:27] op_sel_hi:[0,1,0]
	v_pk_mov_b32 v[154:155], v[154:155], v[150:151] op_sel:[1,0]
	v_pk_mov_b32 v[180:181], v[180:181], v[152:153] op_sel:[1,0]
	v_pk_fma_f32 v[154:155], v[14:15], v[154:155], v[184:185] op_sel_hi:[0,1,1]
	v_pk_fma_f32 v[180:181], v[2:3], v[180:181], v[188:189] op_sel_hi:[0,1,1]
	v_lshlrev_b32_e32 v12, 16, v113
	v_lshlrev_b32_e32 v13, 16, v115
	v_lshlrev_b32_e32 v16, 16, v111
	v_lshlrev_b32_e32 v17, 16, v119
	v_pk_fma_f32 v[154:155], v[10:11], v[150:151], v[154:155] op_sel_hi:[0,1,1]
	v_pk_fma_f32 v[180:181], v[6:7], v[152:153], v[180:181] op_sel_hi:[0,1,1]
	v_pk_mul_f32 v[154:155], v[154:155], v[180:181]
	v_pk_fma_f32 v[180:181], v[22:23], v[150:151], v[30:31] op_sel_hi:[0,1,0]
	v_pk_fma_f32 v[184:185], v[18:19], v[152:153], v[26:27] op_sel_hi:[0,1,0]
	v_pk_mov_b32 v[150:151], v[150:151], v[12:13] op_sel:[1,0]
	v_pk_mov_b32 v[152:153], v[152:153], v[16:17] op_sel:[1,0]
	v_pk_fma_f32 v[150:151], v[14:15], v[150:151], v[180:181] op_sel_hi:[0,1,1]
	v_pk_fma_f32 v[152:153], v[2:3], v[152:153], v[184:185] op_sel_hi:[0,1,1]
	v_lshlrev_b32_e32 v25, 16, v121
	v_mov_b32_e32 v24, v13
	v_lshlrev_b32_e32 v149, 16, v117
	v_mov_b32_e32 v148, v17
	v_pk_fma_f32 v[150:151], v[10:11], v[12:13], v[150:151] op_sel_hi:[0,1,1]
	v_pk_fma_f32 v[152:153], v[6:7], v[16:17], v[152:153] op_sel_hi:[0,1,1]
	v_pk_fma_f32 v[12:13], v[22:23], v[12:13], v[30:31] op_sel_hi:[0,1,0]
	v_pk_fma_f32 v[16:17], v[18:19], v[16:17], v[26:27] op_sel_hi:[0,1,0]
	v_lshlrev_b32_e32 v21, 16, v125
	v_lshlrev_b32_e32 v29, 16, v127
	v_mov_b32_e32 v20, v25
	v_pk_fma_f32 v[12:13], v[14:15], v[24:25], v[12:13] op_sel_hi:[0,1,1]
	v_mov_b32_e32 v28, v149
	v_pk_fma_f32 v[16:17], v[2:3], v[148:149], v[16:17] op_sel_hi:[0,1,1]
	v_pk_fma_f32 v[12:13], v[10:11], v[20:21], v[12:13] op_sel_hi:[0,1,1]
	v_pk_fma_f32 v[16:17], v[6:7], v[28:29], v[16:17] op_sel_hi:[0,1,1]
	v_and_b32_e32 v67, 0xffff0000, v67
	v_and_b32_e32 v66, 0xffff0000, v65
	v_and_b32_e32 v65, 0xffff0000, v69
	v_and_b32_e32 v64, 0xffff0000, v63
	v_and_b32_e32 v61, 0xffff0000, v61
	v_and_b32_e32 v60, 0xffff0000, v55
	v_and_b32_e32 v55, 0xffff0000, v59
	v_and_b32_e32 v54, 0xffff0000, v57
	v_mov_b32_e32 v2, v23
	v_mov_b32_e32 v6, v31
	v_mov_b32_e32 v10, v19
	v_mov_b32_e32 v14, v27
	v_pk_fma_f32 v[22:23], v[2:3], v[60:61], v[6:7] op_sel_hi:[0,1,0]
	v_pk_fma_f32 v[18:19], v[10:11], v[54:55], v[14:15] op_sel_hi:[0,1,0]
	v_mov_b32_e32 v26, v15
	v_pk_mov_b32 v[30:31], v[60:61], v[66:67] op_sel:[1,0]
	v_mov_b32_e32 v48, v3
	v_pk_mov_b32 v[54:55], v[54:55], v[64:65] op_sel:[1,0]
	v_pk_fma_f32 v[22:23], v[26:27], v[30:31], v[22:23] op_sel_hi:[0,1,1]
	v_mov_b32_e32 v30, v11
	v_pk_fma_f32 v[18:19], v[48:49], v[54:55], v[18:19] op_sel_hi:[0,1,1]
	v_mov_b32_e32 v54, v7
	v_and_b32_e32 v77, 0xffff0000, v77
	v_and_b32_e32 v76, 0xffff0000, v73
	v_pk_fma_f32 v[22:23], v[30:31], v[66:67], v[22:23] op_sel_hi:[0,1,1]
	v_pk_fma_f32 v[18:19], v[54:55], v[64:65], v[18:19] op_sel_hi:[0,1,1]
	v_and_b32_e32 v73, 0xffff0000, v75
	v_and_b32_e32 v72, 0xffff0000, v71
	v_pk_mul_f32 v[18:19], v[22:23], v[18:19]
	v_pk_fma_f32 v[22:23], v[2:3], v[66:67], v[6:7] op_sel_hi:[0,1,0]
	v_pk_mov_b32 v[58:59], v[66:67], v[76:77] op_sel:[1,0]
	v_pk_fma_f32 v[56:57], v[10:11], v[64:65], v[14:15] op_sel_hi:[0,1,0]
	v_pk_fma_f32 v[22:23], v[26:27], v[58:59], v[22:23] op_sel_hi:[0,1,1]
	v_pk_mov_b32 v[58:59], v[64:65], v[72:73] op_sel:[1,0]
	v_and_b32_e32 v83, 0xffff0000, v83
	v_pk_fma_f32 v[56:57], v[48:49], v[58:59], v[56:57] op_sel_hi:[0,1,1]
	v_and_b32_e32 v82, 0xffff0000, v81
	v_pk_fma_f32 v[22:23], v[30:31], v[76:77], v[22:23] op_sel_hi:[0,1,1]
	v_pk_fma_f32 v[56:57], v[54:55], v[72:73], v[56:57] op_sel_hi:[0,1,1]
	v_and_b32_e32 v81, 0xffff0000, v85
	v_and_b32_e32 v80, 0xffff0000, v79
	v_pk_mul_f32 v[22:23], v[22:23], v[56:57]
	v_pk_fma_f32 v[56:57], v[2:3], v[76:77], v[6:7] op_sel_hi:[0,1,0]
	v_pk_mov_b32 v[60:61], v[76:77], v[82:83] op_sel:[1,0]
	v_pk_fma_f32 v[58:59], v[10:11], v[72:73], v[14:15] op_sel_hi:[0,1,0]
	v_pk_fma_f32 v[56:57], v[26:27], v[60:61], v[56:57] op_sel_hi:[0,1,1]
	v_pk_mov_b32 v[60:61], v[72:73], v[80:81] op_sel:[1,0]
	v_and_b32_e32 v93, 0xffff0000, v93
	v_pk_fma_f32 v[58:59], v[48:49], v[60:61], v[58:59] op_sel_hi:[0,1,1]
	v_and_b32_e32 v92, 0xffff0000, v89
	v_pk_fma_f32 v[56:57], v[30:31], v[82:83], v[56:57] op_sel_hi:[0,1,1]
	v_pk_fma_f32 v[58:59], v[54:55], v[80:81], v[58:59] op_sel_hi:[0,1,1]
	v_and_b32_e32 v89, 0xffff0000, v91
	v_and_b32_e32 v88, 0xffff0000, v87
	v_pk_mul_f32 v[56:57], v[56:57], v[58:59]
	v_pk_fma_f32 v[58:59], v[2:3], v[82:83], v[6:7] op_sel_hi:[0,1,0]
	v_pk_mov_b32 v[62:63], v[82:83], v[92:93] op_sel:[1,0]
	v_pk_fma_f32 v[60:61], v[10:11], v[80:81], v[14:15] op_sel_hi:[0,1,0]
	v_pk_fma_f32 v[58:59], v[26:27], v[62:63], v[58:59] op_sel_hi:[0,1,1]
	v_pk_mov_b32 v[62:63], v[80:81], v[88:89] op_sel:[1,0]
	v_and_b32_e32 v99, 0xffff0000, v99
	v_pk_fma_f32 v[60:61], v[48:49], v[62:63], v[60:61] op_sel_hi:[0,1,1]
	v_and_b32_e32 v98, 0xffff0000, v97
	v_pk_fma_f32 v[58:59], v[30:31], v[92:93], v[58:59] op_sel_hi:[0,1,1]
	v_pk_fma_f32 v[60:61], v[54:55], v[88:89], v[60:61] op_sel_hi:[0,1,1]
	v_and_b32_e32 v97, 0xffff0000, v101
	v_and_b32_e32 v96, 0xffff0000, v95
	v_pk_mul_f32 v[58:59], v[58:59], v[60:61]
	v_pk_fma_f32 v[60:61], v[2:3], v[92:93], v[6:7] op_sel_hi:[0,1,0]
	v_pk_mov_b32 v[64:65], v[92:93], v[98:99] op_sel:[1,0]
	v_pk_fma_f32 v[62:63], v[10:11], v[88:89], v[14:15] op_sel_hi:[0,1,0]
	v_pk_fma_f32 v[60:61], v[26:27], v[64:65], v[60:61] op_sel_hi:[0,1,1]
	v_pk_mov_b32 v[64:65], v[88:89], v[96:97] op_sel:[1,0]
	v_and_b32_e32 v109, 0xffff0000, v109
	v_pk_fma_f32 v[62:63], v[48:49], v[64:65], v[62:63] op_sel_hi:[0,1,1]
	v_and_b32_e32 v108, 0xffff0000, v105
	v_pk_fma_f32 v[60:61], v[30:31], v[98:99], v[60:61] op_sel_hi:[0,1,1]
	v_pk_fma_f32 v[62:63], v[54:55], v[96:97], v[62:63] op_sel_hi:[0,1,1]
	v_and_b32_e32 v105, 0xffff0000, v107
	v_and_b32_e32 v104, 0xffff0000, v103
	v_pk_mul_f32 v[60:61], v[60:61], v[62:63]
	v_pk_fma_f32 v[62:63], v[2:3], v[98:99], v[6:7] op_sel_hi:[0,1,0]
	v_pk_mov_b32 v[66:67], v[98:99], v[108:109] op_sel:[1,0]
	v_pk_fma_f32 v[64:65], v[10:11], v[96:97], v[14:15] op_sel_hi:[0,1,0]
	v_pk_fma_f32 v[62:63], v[26:27], v[66:67], v[62:63] op_sel_hi:[0,1,1]
	v_pk_mov_b32 v[66:67], v[96:97], v[104:105] op_sel:[1,0]
	v_pk_mul_f32 v[20:21], v[12:13], v[16:17]
	v_pk_fma_f32 v[64:65], v[48:49], v[66:67], v[64:65] op_sel_hi:[0,1,1]
	v_and_b32_e32 v13, 0xffff0000, v115
	v_and_b32_e32 v12, 0xffff0000, v113
	v_and_b32_e32 v25, 0xffff0000, v119
	v_and_b32_e32 v24, 0xffff0000, v111
	v_pk_fma_f32 v[62:63], v[30:31], v[108:109], v[62:63] op_sel_hi:[0,1,1]
	v_pk_fma_f32 v[64:65], v[54:55], v[104:105], v[64:65] op_sel_hi:[0,1,1]
	v_and_b32_e32 v17, 0xffff0000, v121
	v_mov_b32_e32 v16, v13
	v_and_b32_e32 v29, 0xffff0000, v117
	v_mov_b32_e32 v28, v25
	v_pk_mul_f32 v[62:63], v[62:63], v[64:65]
	v_pk_fma_f32 v[64:65], v[2:3], v[108:109], v[6:7] op_sel_hi:[0,1,0]
	v_pk_mov_b32 v[68:69], v[108:109], v[12:13] op_sel:[1,0]
	v_pk_fma_f32 v[2:3], v[2:3], v[12:13], v[6:7] op_sel_hi:[0,1,0]
	v_pk_fma_f32 v[6:7], v[10:11], v[24:25], v[14:15] op_sel_hi:[0,1,0]
	v_and_b32_e32 v111, 0xffff0000, v125
	v_mov_b32_e32 v110, v17
	v_and_b32_e32 v113, 0xffff0000, v127
	v_mov_b32_e32 v112, v29
	v_pk_fma_f32 v[66:67], v[10:11], v[104:105], v[14:15] op_sel_hi:[0,1,0]
	v_pk_fma_f32 v[64:65], v[26:27], v[68:69], v[64:65] op_sel_hi:[0,1,1]
	v_pk_mov_b32 v[68:69], v[104:105], v[24:25] op_sel:[1,0]
	v_pk_fma_f32 v[2:3], v[26:27], v[16:17], v[2:3] op_sel_hi:[0,1,1]
	v_pk_fma_f32 v[6:7], v[48:49], v[28:29], v[6:7] op_sel_hi:[0,1,1]
	v_pk_fma_f32 v[66:67], v[48:49], v[68:69], v[66:67] op_sel_hi:[0,1,1]
	v_pk_fma_f32 v[2:3], v[30:31], v[110:111], v[2:3] op_sel_hi:[0,1,1]
	v_pk_fma_f32 v[6:7], v[54:55], v[112:113], v[6:7] op_sel_hi:[0,1,1]
	v_or_b32_e32 v122, 15, v52
	v_pk_fma_f32 v[66:67], v[54:55], v[24:25], v[66:67] op_sel_hi:[0,1,1]
	v_pk_mul_f32 v[24:25], v[2:3], v[6:7]
	v_lshlrev_b64 v[6:7], 11, v[122:123]
	v_pk_fma_f32 v[64:65], v[30:31], v[12:13], v[64:65] op_sel_hi:[0,1,1]
	v_cvt_pk_bf16_f32 v2, v32, v33
	v_cvt_pk_bf16_f32 v3, v34, v35
	v_lshl_add_u64 v[6:7], v[128:129], 0, v[6:7]
	v_cvt_pk_bf16_f32 v10, v36, v37
	v_cvt_pk_bf16_f32 v11, v38, v39
	v_cvt_pk_bf16_f32 v12, v40, v41
	v_cvt_pk_bf16_f32 v13, v42, v43
	v_cvt_pk_bf16_f32 v17, v132, v133
	v_pk_mul_f32 v[150:151], v[150:151], v[152:153]
	global_store_dwordx2 v[6:7], v[2:3], off nt
	v_cvt_pk_bf16_f32 v14, v44, v45
	v_cvt_pk_bf16_f32 v15, v46, v47
	v_cvt_pk_bf16_f32 v16, v130, v131
	ds_write_b128 v176, v[10:13]
	ds_write_b128 v176, v[14:17] offset:16
	v_cvt_pk_bf16_f32 v10, v134, v135
	v_cvt_pk_bf16_f32 v11, v136, v137
	v_cvt_pk_bf16_f32 v12, v138, v139
	v_cvt_pk_bf16_f32 v13, v140, v141
	v_cvt_pk_bf16_f32 v17, v0, v1
	v_cvt_pk_bf16_f32 v0, v4, v5
	v_cvt_pk_bf16_f32 v1, v8, v9
	v_cvt_pk_bf16_f32 v2, v190, v191
	v_cvt_pk_bf16_f32 v3, v186, v187
	v_pk_mul_f32 v[64:65], v[64:65], v[66:67]
	v_cvt_pk_bf16_f32 v14, v142, v143
	v_cvt_pk_bf16_f32 v15, v144, v145
	v_cvt_pk_bf16_f32 v16, v146, v147
	ds_write_b128 v176, v[10:13] offset:144
	ds_write_b128 v176, v[14:17] offset:160
	v_cvt_pk_bf16_f32 v4, v182, v183
	v_cvt_pk_bf16_f32 v5, v154, v155
	v_cvt_pk_bf16_f32 v6, v150, v151
	v_cvt_pk_bf16_f32 v7, v20, v21
	ds_write_b128 v176, v[0:3] offset:288
	ds_write_b128 v176, v[4:7] offset:304
	v_cvt_pk_bf16_f32 v0, v18, v19
	v_cvt_pk_bf16_f32 v1, v22, v23
	v_cvt_pk_bf16_f32 v2, v56, v57
	v_cvt_pk_bf16_f32 v3, v58, v59
	v_cvt_pk_bf16_f32 v4, v60, v61
	v_cvt_pk_bf16_f32 v5, v62, v63
	v_cvt_pk_bf16_f32 v6, v64, v65
	v_cvt_pk_bf16_f32 v7, v24, v25
	ds_write_b128 v176, v[0:3] offset:432
	ds_write_b128 v176, v[4:7] offset:448
	s_waitcnt lgkmcnt(0)
	ds_read2_b64 v[0:3], v177 offset1:72
	v_or_b32_e32 v6, s47, v156
	v_lshlrev_b32_e32 v48, 2, v6
	v_lshl_add_u64 v[6:7], v[48:49], 0, s[36:37]
	v_lshl_add_u64 v[4:5], v[50:51], 0, s[8:9]
	v_lshlrev_b64 v[6:7], 14, v[6:7]
	v_lshl_add_u64 v[6:7], v[4:5], 0, v[6:7]
	s_waitcnt lgkmcnt(0)
	global_store_dwordx2 v[6:7], v[0:1], off nt
	v_or_b32_e32 v0, s47, v160
	v_lshlrev_b32_e32 v48, 2, v0
	v_lshl_add_u64 v[0:1], v[48:49], 0, s[36:37]
	v_lshlrev_b64 v[0:1], 14, v[0:1]
	v_lshl_add_u64 v[0:1], v[4:5], 0, v[0:1]
	global_store_dwordx2 v[0:1], v[2:3], off nt
	ds_read2_b64 v[0:3], v177 offset0:144 offset1:216
	v_or_b32_e32 v6, s47, v161
	v_lshlrev_b32_e32 v48, 2, v6
	v_lshl_add_u64 v[6:7], v[48:49], 0, s[36:37]
	v_lshlrev_b64 v[6:7], 14, v[6:7]
	v_lshl_add_u64 v[6:7], v[4:5], 0, v[6:7]
	s_waitcnt lgkmcnt(0)
	global_store_dwordx2 v[6:7], v[0:1], off nt
	v_or_b32_e32 v0, s47, v162
	v_lshlrev_b32_e32 v48, 2, v0
	v_lshl_add_u64 v[0:1], v[48:49], 0, s[36:37]
	v_lshlrev_b64 v[0:1], 14, v[0:1]
	v_lshl_add_u64 v[0:1], v[4:5], 0, v[0:1]
	v_add_u32_e32 v8, 0x800, v177
	global_store_dwordx2 v[0:1], v[2:3], off nt
	ds_read2_b64 v[0:3], v8 offset0:32 offset1:104
	v_or_b32_e32 v6, s47, v163
	v_lshlrev_b32_e32 v48, 2, v6
	v_lshl_add_u64 v[6:7], v[48:49], 0, s[36:37]
	v_lshlrev_b64 v[6:7], 14, v[6:7]
	v_lshl_add_u64 v[6:7], v[4:5], 0, v[6:7]
	s_waitcnt lgkmcnt(0)
	global_store_dwordx2 v[6:7], v[0:1], off nt
	v_or_b32_e32 v0, s47, v164
	v_lshlrev_b32_e32 v48, 2, v0
	v_lshl_add_u64 v[0:1], v[48:49], 0, s[36:37]
	v_lshlrev_b64 v[0:1], 14, v[0:1]
	v_lshl_add_u64 v[0:1], v[4:5], 0, v[0:1]
	global_store_dwordx2 v[0:1], v[2:3], off nt
	ds_read2_b64 v[0:3], v8 offset0:176 offset1:248
	v_or_b32_e32 v6, s47, v165
	v_lshlrev_b32_e32 v48, 2, v6
	v_lshl_add_u64 v[6:7], v[48:49], 0, s[36:37]
	v_lshlrev_b64 v[6:7], 14, v[6:7]
	v_lshl_add_u64 v[6:7], v[4:5], 0, v[6:7]
	s_waitcnt lgkmcnt(0)
	global_store_dwordx2 v[6:7], v[0:1], off nt
	v_or_b32_e32 v0, s47, v166
	v_lshlrev_b32_e32 v48, 2, v0
	v_lshl_add_u64 v[0:1], v[48:49], 0, s[36:37]
	v_lshlrev_b64 v[0:1], 14, v[0:1]
	v_lshl_add_u64 v[0:1], v[4:5], 0, v[0:1]
	global_store_dwordx2 v[0:1], v[2:3], off nt
	v_add_u32_e32 v0, 0x1000, v177
	ds_read2_b64 v[0:3], v0 offset0:64 offset1:136
	v_or_b32_e32 v6, s47, v167
	v_lshlrev_b32_e32 v48, 2, v6
	v_lshl_add_u64 v[6:7], v[48:49], 0, s[36:37]
	v_lshlrev_b64 v[6:7], 14, v[6:7]
	v_lshl_add_u64 v[6:7], v[4:5], 0, v[6:7]
	s_waitcnt lgkmcnt(0)
	global_store_dwordx2 v[6:7], v[0:1], off nt
	v_or_b32_e32 v0, s47, v168
	v_lshlrev_b32_e32 v48, 2, v0
	v_lshl_add_u64 v[0:1], v[48:49], 0, s[36:37]
	v_lshlrev_b64 v[0:1], 14, v[0:1]
	v_lshl_add_u64 v[0:1], v[4:5], 0, v[0:1]
	global_store_dwordx2 v[0:1], v[2:3], off nt
	v_add_u32_e32 v0, 0x1400, v177
	ds_read2_b64 v[0:3], v0 offset0:80 offset1:152
	v_or_b32_e32 v6, s47, v169
	v_lshlrev_b32_e32 v48, 2, v6
	v_lshl_add_u64 v[6:7], v[48:49], 0, s[36:37]
	v_lshlrev_b64 v[6:7], 14, v[6:7]
	v_lshl_add_u64 v[6:7], v[4:5], 0, v[6:7]
	s_waitcnt lgkmcnt(0)
	global_store_dwordx2 v[6:7], v[0:1], off nt
	v_or_b32_e32 v0, s47, v171
	v_lshlrev_b32_e32 v48, 2, v0
	v_lshl_add_u64 v[0:1], v[48:49], 0, s[36:37]
	v_lshlrev_b64 v[0:1], 14, v[0:1]
	v_lshl_add_u64 v[0:1], v[4:5], 0, v[0:1]
	global_store_dwordx2 v[0:1], v[2:3], off nt
	v_add_u32_e32 v0, 0x1800, v177
	ds_read2_b64 v[0:3], v0 offset0:96 offset1:168
	v_or_b32_e32 v6, s47, v172
	v_lshlrev_b32_e32 v48, 2, v6
	v_lshl_add_u64 v[6:7], v[48:49], 0, s[36:37]
	v_lshlrev_b64 v[6:7], 14, v[6:7]
	v_lshl_add_u64 v[6:7], v[4:5], 0, v[6:7]
	s_waitcnt lgkmcnt(0)
	global_store_dwordx2 v[6:7], v[0:1], off nt
	v_or_b32_e32 v0, s47, v173
	v_lshlrev_b32_e32 v48, 2, v0
	v_lshl_add_u64 v[0:1], v[48:49], 0, s[36:37]
	v_lshlrev_b64 v[0:1], 14, v[0:1]
	v_lshl_add_u64 v[0:1], v[4:5], 0, v[0:1]
	global_store_dwordx2 v[0:1], v[2:3], off nt
	ds_read_b64 v[0:1], v177 offset:8064
	ds_read_b64 v[6:7], v178
	v_or_b32_e32 v2, s47, v174
	v_lshlrev_b32_e32 v48, 2, v2
	v_lshl_add_u64 v[2:3], v[48:49], 0, s[36:37]
	v_lshlrev_b64 v[2:3], 14, v[2:3]
	v_lshl_add_u64 v[2:3], v[4:5], 0, v[2:3]
	s_waitcnt lgkmcnt(1)
	global_store_dwordx2 v[2:3], v[0:1], off nt
	v_or_b32_e32 v0, s47, v175
	v_lshlrev_b32_e32 v48, 2, v0
	v_lshl_add_u64 v[0:1], v[48:49], 0, s[36:37]
	v_lshlrev_b64 v[0:1], 14, v[0:1]
	v_lshl_add_u64 v[0:1], v[4:5], 0, v[0:1]
	s_waitcnt lgkmcnt(0)
	global_store_dwordx2 v[0:1], v[6:7], off nt
	v_readlane_b32 s36, v247, 42
	s_waitcnt lgkmcnt(0)
	s_add_i32 s33, s33, s36
	s_cmpk_lt_i32 s33, 0x2000
	v_readlane_b32 s37, v247, 43
	s_cbranch_scc0 .LBB0_303

.LBB0_424:
	s_and_b32 s15, s4, 15
	s_ashr_i32 s2, s4, 11
	s_lshl_b32 s18, s15, 8
	s_and_b32 s14, s5, 0x1fc0
	s_ashr_i32 s3, s2, 31
	v_or_b32_e32 v0, s18, v5
	s_lshl_b32 s0, s14, 1
	v_lshl_add_u64 v[8:9], v[0:1], 0, s[2:3]
	v_or_b32_e32 v0, s18, v25
	v_lshl_add_u64 v[48:49], v[2:3], 0, s[0:1]
	v_lshlrev_b64 v[8:9], 14, v[8:9]
	v_lshl_add_u64 v[14:15], v[0:1], 0, s[2:3]
	v_or_b32_e32 v0, s18, v26
	v_lshl_add_u64 v[16:17], v[48:49], 0, v[8:9]
	v_lshlrev_b64 v[8:9], 14, v[14:15]
	v_lshl_add_u64 v[14:15], v[0:1], 0, s[2:3]
	v_or_b32_e32 v0, s18, v27
	v_lshl_add_u64 v[20:21], v[0:1], 0, s[2:3]
	v_or_b32_e32 v0, s18, v28
	v_lshlrev_b64 v[14:15], 14, v[14:15]
	v_lshlrev_b64 v[56:57], 14, v[20:21]
	v_lshl_add_u64 v[58:59], v[0:1], 0, s[2:3]
	v_or_b32_e32 v0, s18, v29
	v_lshl_add_u64 v[54:55], v[48:49], 0, v[14:15]
	v_lshl_add_u64 v[56:57], v[48:49], 0, v[56:57]
	v_lshlrev_b64 v[58:59], 14, v[58:59]
	v_lshl_add_u64 v[60:61], v[0:1], 0, s[2:3]
	v_or_b32_e32 v0, s18, v30
	v_lshl_add_u64 v[18:19], v[48:49], 0, v[8:9]
	global_load_dwordx2 v[50:51], v[16:17], off
	global_load_dwordx2 v[52:53], v[18:19], off
	global_load_dwordx2 v[62:63], v[54:55], off
	global_load_dwordx2 v[64:65], v[56:57], off
	v_lshl_add_u64 v[54:55], v[48:49], 0, v[58:59]
	v_lshlrev_b64 v[56:57], 14, v[60:61]
	v_lshl_add_u64 v[58:59], v[0:1], 0, s[2:3]
	v_or_b32_e32 v0, s18, v31
	v_lshl_add_u64 v[56:57], v[48:49], 0, v[56:57]
	v_lshlrev_b64 v[58:59], 14, v[58:59]
	v_lshl_add_u64 v[60:61], v[0:1], 0, s[2:3]
	v_or_b32_e32 v0, s18, v32
	global_load_dwordx2 v[66:67], v[54:55], off
	global_load_dwordx2 v[68:69], v[56:57], off
	v_lshl_add_u64 v[54:55], v[48:49], 0, v[58:59]
	v_lshlrev_b64 v[56:57], 14, v[60:61]
	v_lshl_add_u64 v[58:59], v[0:1], 0, s[2:3]
	v_or_b32_e32 v0, s18, v33
	v_lshl_add_u64 v[56:57], v[48:49], 0, v[56:57]
	v_lshlrev_b64 v[58:59], 14, v[58:59]
	v_lshl_add_u64 v[60:61], v[0:1], 0, s[2:3]
	v_or_b32_e32 v0, s18, v34
	global_load_dwordx2 v[70:71], v[54:55], off
	global_load_dwordx2 v[72:73], v[56:57], off
	v_lshl_add_u64 v[54:55], v[48:49], 0, v[58:59]
	v_lshlrev_b64 v[56:57], 14, v[60:61]
	v_lshl_add_u64 v[58:59], v[0:1], 0, s[2:3]
	v_or_b32_e32 v0, s18, v35
	v_lshl_add_u64 v[56:57], v[48:49], 0, v[56:57]
	v_lshlrev_b64 v[58:59], 14, v[58:59]
	v_lshl_add_u64 v[60:61], v[0:1], 0, s[2:3]
	v_or_b32_e32 v0, s18, v36
	global_load_dwordx2 v[74:75], v[54:55], off
	global_load_dwordx2 v[76:77], v[56:57], off
	v_lshl_add_u64 v[54:55], v[48:49], 0, v[58:59]
	v_lshlrev_b64 v[56:57], 14, v[60:61]
	v_lshl_add_u64 v[58:59], v[0:1], 0, s[2:3]
	v_or_b32_e32 v0, s18, v37
	v_lshl_add_u64 v[56:57], v[48:49], 0, v[56:57]
	v_lshlrev_b64 v[58:59], 14, v[58:59]
	v_lshl_add_u64 v[60:61], v[0:1], 0, s[2:3]
	v_or_b32_e32 v0, s18, v38
	global_load_dwordx2 v[78:79], v[54:55], off
	global_load_dwordx2 v[80:81], v[56:57], off
	v_lshl_add_u64 v[54:55], v[48:49], 0, v[58:59]
	v_lshlrev_b64 v[56:57], 14, v[60:61]
	v_lshl_add_u64 v[58:59], v[0:1], 0, s[2:3]
	v_or_b32_e32 v0, s18, v39
	v_lshl_add_u64 v[56:57], v[48:49], 0, v[56:57]
	v_lshlrev_b64 v[58:59], 14, v[58:59]
	v_lshl_add_u64 v[60:61], v[0:1], 0, s[2:3]
	global_load_dwordx2 v[82:83], v[54:55], off
	global_load_dwordx2 v[84:85], v[56:57], off
	v_lshl_add_u64 v[54:55], v[48:49], 0, v[58:59]
	v_lshlrev_b64 v[56:57], 14, v[60:61]
	v_lshl_add_u64 v[48:49], v[48:49], 0, v[56:57]
	global_load_dwordx2 v[56:57], v[54:55], off
	global_load_dwordx2 v[58:59], v[48:49], off
	s_lshl_b64 s[16:17], s[2:3], 13
	v_or_b32_e32 v10, s16, v4
	s_lshl_b32 s0, s15, 7
	v_mov_b32_e32 v11, s17
	v_or_b32_e32 v10, s14, v10
	v_lshl_add_u64 v[12:13], v[6:7], 0, s[0:1]
	v_lshlrev_b64 v[10:11], 11, v[10:11]
	v_lshl_add_u64 v[8:9], v[12:13], 0, v[10:11]
	v_add_co_u32_e32 v10, vcc, s7, v8
	s_add_i32 s4, s4, s20
	s_nop 0
	v_addc_co_u32_e32 v11, vcc, 0, v9, vcc
	v_add_co_u32_e32 v18, vcc, s8, v8
	s_add_i32 s5, s5, s6
	s_nop 0
	v_addc_co_u32_e32 v19, vcc, 0, v9, vcc
	v_add_co_u32_e32 v12, vcc, s9, v8
	s_cmpk_lt_i32 s4, 0x2000
	s_nop 0
	v_addc_co_u32_e32 v13, vcc, 0, v9, vcc
	v_add_co_u32_e32 v20, vcc, s10, v8
	s_waitcnt vmcnt(14)
	ds_write2_b64 v40, v[50:51], v[52:53] offset1:72
	s_waitcnt vmcnt(12)
	ds_write2_b64 v40, v[62:63], v[64:65] offset0:144 offset1:216
	s_waitcnt vmcnt(10)
	ds_write2_b64 v43, v[66:67], v[68:69] offset0:32 offset1:104
	s_waitcnt vmcnt(8)
	ds_write2_b64 v43, v[70:71], v[72:73] offset0:176 offset1:248
	s_waitcnt vmcnt(6)
	ds_write2_b64 v44, v[74:75], v[76:77] offset0:64 offset1:136
	s_waitcnt vmcnt(4)
	ds_write2_b64 v45, v[78:79], v[80:81] offset0:80 offset1:152
	s_waitcnt vmcnt(2)
	ds_write2_b64 v46, v[82:83], v[84:85] offset0:96 offset1:168
	s_waitcnt vmcnt(1)
	ds_write_b64 v40, v[56:57] offset:8064
	s_waitcnt vmcnt(0)
	ds_write_b64 v41, v[58:59]
	v_addc_co_u32_e32 v21, vcc, 0, v9, vcc
	v_add_co_u32_e32 v14, vcc, s11, v8
	s_waitcnt lgkmcnt(0)
	ds_read_b128 v[48:51], v42
	ds_read_b128 v[52:55], v42 offset:16
	ds_read_b128 v[56:59], v42 offset:144
	ds_read_b128 v[60:63], v42 offset:160
	ds_read_b128 v[64:67], v42 offset:288
	ds_read_b128 v[68:71], v42 offset:304
	ds_read_b128 v[72:75], v42 offset:432
	ds_read_b128 v[76:79], v42 offset:448
	v_addc_co_u32_e32 v15, vcc, 0, v9, vcc
	v_add_co_u32_e32 v22, vcc, s12, v8
	s_waitcnt lgkmcnt(5)
	v_lshlrev_b32_e32 v113, 16, v56
	v_addc_co_u32_e32 v23, vcc, 0, v9, vcc
	v_add_co_u32_e32 v16, vcc, s13, v8
	v_lshlrev_b32_e32 v112, 16, v48
	s_nop 0
	v_addc_co_u32_e32 v17, vcc, 0, v9, vcc
	global_load_dwordx2 v[80:81], v[8:9], off
	global_load_dwordx2 v[82:83], v[18:19], off offset:-4096
	global_load_dwordx2 v[84:85], v[8:9], off offset:2048
	global_load_dwordx2 v[86:87], v[10:11], off offset:2048
	global_load_dwordx2 v[88:89], v[12:13], off offset:2048
	global_load_dwordx2 v[90:91], v[18:19], off
	global_load_dwordx2 v[92:93], v[18:19], off offset:2048
	global_load_dwordx2 v[94:95], v[20:21], off offset:-4096
	global_load_dwordx2 v[96:97], v[20:21], off
	global_load_dwordx2 v[98:99], v[20:21], off offset:2048
	global_load_dwordx2 v[100:101], v[22:23], off offset:-4096
	global_load_dwordx2 v[102:103], v[22:23], off
	global_load_dwordx2 v[104:105], v[22:23], off offset:2048
	global_load_dwordx2 v[106:107], v[14:15], off offset:2048
	global_load_dwordx2 v[108:109], v[16:17], off
	global_load_dwordx2 v[110:111], v[16:17], off offset:2048
	s_waitcnt lgkmcnt(1)
	v_lshlrev_b32_e32 v115, 16, v72
	v_lshlrev_b32_e32 v114, 16, v64
	v_and_b32_e32 v117, 0xffff0000, v56
	v_and_b32_e32 v116, 0xffff0000, v48
	v_and_b32_e32 v119, 0xffff0000, v72
	v_and_b32_e32 v118, 0xffff0000, v64
	v_lshlrev_b32_e32 v120, 16, v49
	v_lshlrev_b32_e32 v123, 16, v73
	v_lshlrev_b32_e32 v122, 16, v65
	v_and_b32_e32 v56, 0xffff0000, v49
	v_and_b32_e32 v49, 0xffff0000, v73
	v_and_b32_e32 v48, 0xffff0000, v65
	v_lshlrev_b32_e32 v65, 16, v58
	v_lshlrev_b32_e32 v64, 16, v50
	v_lshlrev_b32_e32 v73, 16, v74
	v_lshlrev_b32_e32 v72, 16, v66
	v_and_b32_e32 v125, 0xffff0000, v58
	v_and_b32_e32 v124, 0xffff0000, v50
	v_and_b32_e32 v127, 0xffff0000, v74
	v_and_b32_e32 v126, 0xffff0000, v66
	v_lshlrev_b32_e32 v128, 16, v51
	v_lshlrev_b32_e32 v131, 16, v75
	v_lshlrev_b32_e32 v130, 16, v67
	v_and_b32_e32 v58, 0xffff0000, v51
	v_and_b32_e32 v51, 0xffff0000, v75
	v_and_b32_e32 v50, 0xffff0000, v67
	v_lshlrev_b32_e32 v67, 16, v60
	v_lshlrev_b32_e32 v66, 16, v52
	s_waitcnt lgkmcnt(0)
	v_lshlrev_b32_e32 v75, 16, v76
	v_lshlrev_b32_e32 v74, 16, v68
	v_and_b32_e32 v133, 0xffff0000, v60
	v_and_b32_e32 v132, 0xffff0000, v52
	v_and_b32_e32 v135, 0xffff0000, v76
	v_and_b32_e32 v134, 0xffff0000, v68
	v_lshlrev_b32_e32 v136, 16, v53
	v_lshlrev_b32_e32 v139, 16, v77
	v_lshlrev_b32_e32 v138, 16, v69
	v_and_b32_e32 v60, 0xffff0000, v53
	v_and_b32_e32 v53, 0xffff0000, v77
	v_and_b32_e32 v52, 0xffff0000, v69
	v_lshlrev_b32_e32 v69, 16, v62
	v_lshlrev_b32_e32 v68, 16, v54
	v_lshlrev_b32_e32 v77, 16, v78
	v_lshlrev_b32_e32 v76, 16, v70
	v_and_b32_e32 v141, 0xffff0000, v62
	v_and_b32_e32 v140, 0xffff0000, v54
	v_and_b32_e32 v143, 0xffff0000, v78
	v_and_b32_e32 v142, 0xffff0000, v70
	v_lshlrev_b32_e32 v144, 16, v55
	v_lshlrev_b32_e32 v147, 16, v79
	v_lshlrev_b32_e32 v146, 16, v71
	v_and_b32_e32 v62, 0xffff0000, v55
	v_and_b32_e32 v55, 0xffff0000, v79
	v_and_b32_e32 v54, 0xffff0000, v71
	v_lshlrev_b32_e32 v121, 16, v57
	v_and_b32_e32 v57, 0xffff0000, v57
	v_lshlrev_b32_e32 v129, 16, v59
	v_and_b32_e32 v59, 0xffff0000, v59
	v_lshlrev_b32_e32 v137, 16, v61
	v_and_b32_e32 v61, 0xffff0000, v61
	v_lshlrev_b32_e32 v145, 16, v63
	v_and_b32_e32 v63, 0xffff0000, v63
	s_waitcnt vmcnt(15)
	v_lshlrev_b32_e32 v70, 16, v80
	v_and_b32_e32 v71, 0xffff0000, v80
	v_lshlrev_b32_e32 v78, 16, v81
	v_and_b32_e32 v79, 0xffff0000, v81
	s_waitcnt vmcnt(13)
	v_lshlrev_b32_e32 v80, 16, v84
	v_and_b32_e32 v81, 0xffff0000, v84
	v_lshlrev_b32_e32 v84, 16, v85
	v_and_b32_e32 v85, 0xffff0000, v85
	v_lshlrev_b32_e32 v148, 16, v82
	v_and_b32_e32 v149, 0xffff0000, v82
	v_lshlrev_b32_e32 v82, 16, v83
	v_and_b32_e32 v83, 0xffff0000, v83
	s_waitcnt vmcnt(12)
	v_lshlrev_b32_e32 v150, 16, v86
	v_and_b32_e32 v151, 0xffff0000, v86
	v_lshlrev_b32_e32 v86, 16, v87
	v_and_b32_e32 v87, 0xffff0000, v87
	s_waitcnt vmcnt(10)
	v_lshlrev_b32_e32 v152, 16, v90
	v_and_b32_e32 v153, 0xffff0000, v90
	v_lshlrev_b32_e32 v90, 16, v91
	v_and_b32_e32 v91, 0xffff0000, v91
	s_waitcnt vmcnt(9)
	v_lshlrev_b32_e32 v154, 16, v92
	v_and_b32_e32 v155, 0xffff0000, v92
	v_lshlrev_b32_e32 v92, 16, v93
	v_and_b32_e32 v93, 0xffff0000, v93
	s_waitcnt vmcnt(8)
	v_lshlrev_b32_e32 v156, 16, v94
	v_and_b32_e32 v157, 0xffff0000, v94
	v_lshlrev_b32_e32 v94, 16, v95
	v_and_b32_e32 v95, 0xffff0000, v95
	v_lshlrev_b32_e32 v158, 16, v88
	v_and_b32_e32 v159, 0xffff0000, v88
	v_lshlrev_b32_e32 v88, 16, v89
	v_and_b32_e32 v89, 0xffff0000, v89
	s_waitcnt vmcnt(7)
	v_lshlrev_b32_e32 v160, 16, v96
	v_and_b32_e32 v161, 0xffff0000, v96
	v_lshlrev_b32_e32 v96, 16, v97
	v_and_b32_e32 v97, 0xffff0000, v97
	s_waitcnt vmcnt(6)
	v_lshlrev_b32_e32 v162, 16, v98
	v_and_b32_e32 v163, 0xffff0000, v98
	v_lshlrev_b32_e32 v98, 16, v99
	v_and_b32_e32 v99, 0xffff0000, v99
	s_waitcnt vmcnt(5)
	v_lshlrev_b32_e32 v164, 16, v100
	v_and_b32_e32 v165, 0xffff0000, v100
	v_lshlrev_b32_e32 v100, 16, v101
	v_and_b32_e32 v101, 0xffff0000, v101
	s_waitcnt vmcnt(2)
	v_lshlrev_b32_e32 v166, 16, v106
	v_and_b32_e32 v167, 0xffff0000, v106
	v_lshlrev_b32_e32 v106, 16, v107
	v_and_b32_e32 v107, 0xffff0000, v107
	v_lshlrev_b32_e32 v168, 16, v102
	v_and_b32_e32 v169, 0xffff0000, v102
	v_lshlrev_b32_e32 v102, 16, v103
	v_and_b32_e32 v103, 0xffff0000, v103
	v_lshlrev_b32_e32 v172, 16, v104
	v_and_b32_e32 v173, 0xffff0000, v104
	v_lshlrev_b32_e32 v104, 16, v105
	v_and_b32_e32 v105, 0xffff0000, v105
	s_waitcnt vmcnt(1)
	v_lshlrev_b32_e32 v174, 16, v108
	v_and_b32_e32 v175, 0xffff0000, v108
	v_lshlrev_b32_e32 v108, 16, v109
	v_and_b32_e32 v109, 0xffff0000, v109
	s_waitcnt vmcnt(0)
	v_lshlrev_b32_e32 v176, 16, v110
	v_and_b32_e32 v177, 0xffff0000, v110
	v_lshlrev_b32_e32 v110, 16, v111
	v_and_b32_e32 v111, 0xffff0000, v111
	v_pk_mul_f32 v[70:71], v[112:113], v[70:71]
	v_pk_mul_f32 v[78:79], v[114:115], v[78:79]
	v_pk_mul_f32 v[80:81], v[116:117], v[80:81]
	v_pk_mul_f32 v[84:85], v[118:119], v[84:85]
	v_pk_mul_f32 v[112:113], v[120:121], v[148:149]
	v_pk_mul_f32 v[82:83], v[122:123], v[82:83]
	v_pk_mul_f32 v[56:57], v[56:57], v[150:151]
	v_pk_mul_f32 v[48:49], v[48:49], v[86:87]
	v_pk_mul_f32 v[64:65], v[64:65], v[152:153]
	v_pk_mul_f32 v[72:73], v[72:73], v[90:91]
	v_pk_mul_f32 v[86:87], v[124:125], v[154:155]
	v_pk_mul_f32 v[90:91], v[126:127], v[92:93]
	v_pk_mul_f32 v[92:93], v[128:129], v[156:157]
	v_pk_mul_f32 v[94:95], v[130:131], v[94:95]
	v_pk_mul_f32 v[58:59], v[58:59], v[158:159]
	v_pk_mul_f32 v[50:51], v[50:51], v[88:89]
	v_pk_mul_f32 v[66:67], v[66:67], v[160:161]
	v_pk_mul_f32 v[74:75], v[74:75], v[96:97]
	v_pk_mul_f32 v[88:89], v[132:133], v[162:163]
	v_pk_mul_f32 v[96:97], v[134:135], v[98:99]
	v_pk_mul_f32 v[98:99], v[136:137], v[164:165]
	v_pk_mul_f32 v[100:101], v[138:139], v[100:101]
	v_pk_mul_f32 v[60:61], v[60:61], v[166:167]
	v_pk_mul_f32 v[52:53], v[52:53], v[106:107]
	v_pk_mul_f32 v[68:69], v[68:69], v[168:169]
	v_pk_mul_f32 v[76:77], v[76:77], v[102:103]
	v_pk_mul_f32 v[102:103], v[140:141], v[172:173]
	v_pk_mul_f32 v[104:105], v[142:143], v[104:105]
	v_pk_mul_f32 v[106:107], v[144:145], v[174:175]
	v_pk_mul_f32 v[108:109], v[146:147], v[108:109]
	v_pk_mul_f32 v[62:63], v[62:63], v[176:177]
	v_pk_mul_f32 v[54:55], v[54:55], v[110:111]
	v_cvt_pk_bf16_f32 v70, v70, v71
	v_cvt_pk_bf16_f32 v71, v78, v79
	v_cvt_pk_bf16_f32 v78, v80, v81
	v_cvt_pk_bf16_f32 v79, v84, v85
	v_cvt_pk_bf16_f32 v80, v112, v113
	v_cvt_pk_bf16_f32 v81, v82, v83
	v_cvt_pk_bf16_f32 v56, v56, v57
	v_cvt_pk_bf16_f32 v57, v48, v49
	v_cvt_pk_bf16_f32 v48, v64, v65
	v_cvt_pk_bf16_f32 v49, v72, v73
	v_cvt_pk_bf16_f32 v64, v86, v87
	v_cvt_pk_bf16_f32 v65, v90, v91
	v_cvt_pk_bf16_f32 v72, v92, v93
	v_cvt_pk_bf16_f32 v73, v94, v95
	v_cvt_pk_bf16_f32 v58, v58, v59
	v_cvt_pk_bf16_f32 v59, v50, v51
	v_cvt_pk_bf16_f32 v50, v66, v67
	v_cvt_pk_bf16_f32 v51, v74, v75
	v_cvt_pk_bf16_f32 v66, v88, v89
	v_cvt_pk_bf16_f32 v67, v96, v97
	v_cvt_pk_bf16_f32 v74, v98, v99
	v_cvt_pk_bf16_f32 v75, v100, v101
	v_cvt_pk_bf16_f32 v60, v60, v61
	v_cvt_pk_bf16_f32 v61, v52, v53
	v_cvt_pk_bf16_f32 v52, v68, v69
	v_cvt_pk_bf16_f32 v53, v76, v77
	v_cvt_pk_bf16_f32 v68, v102, v103
	v_cvt_pk_bf16_f32 v69, v104, v105
	v_cvt_pk_bf16_f32 v76, v106, v107
	v_cvt_pk_bf16_f32 v77, v108, v109
	v_cvt_pk_bf16_f32 v62, v62, v63
	v_cvt_pk_bf16_f32 v63, v54, v55
	global_store_dwordx2 v[8:9], v[70:71], off nt
	global_store_dwordx2 v[8:9], v[78:79], off offset:2048 nt
	global_store_dwordx2 v[18:19], v[80:81], off offset:-4096 nt
	global_store_dwordx2 v[10:11], v[56:57], off offset:2048 nt
	global_store_dwordx2 v[18:19], v[48:49], off nt
	global_store_dwordx2 v[18:19], v[64:65], off offset:2048 nt
	global_store_dwordx2 v[20:21], v[72:73], off offset:-4096 nt
	global_store_dwordx2 v[12:13], v[58:59], off offset:2048 nt
	global_store_dwordx2 v[20:21], v[50:51], off nt
	global_store_dwordx2 v[20:21], v[66:67], off offset:2048 nt
	global_store_dwordx2 v[22:23], v[74:75], off offset:-4096 nt
	global_store_dwordx2 v[14:15], v[60:61], off offset:2048 nt
	global_store_dwordx2 v[22:23], v[52:53], off nt
	global_store_dwordx2 v[22:23], v[68:69], off offset:2048 nt
	global_store_dwordx2 v[16:17], v[76:77], off nt
	global_store_dwordx2 v[16:17], v[62:63], off offset:2048 nt
	s_waitcnt lgkmcnt(0)
	s_cbranch_scc1 .LBB0_424

.Lscan_vtj_0:
	ds_read_b128 v[240:243], v154 offset:40960
	s_waitcnt lgkmcnt(2)
	v_mfma_f32_16x16x32_bf16 v[200:203], v[108:111], v[184:187], 0
	v_mfma_f32_16x16x32_bf16 v[204:207], v[108:111], v[188:191], 0
	v_mfma_f32_16x16x32_bf16 v[200:203], v[112:115], v[192:195], v[200:203]
	v_mfma_f32_16x16x32_bf16 v[204:207], v[112:115], v[196:199], v[204:207]
	v_lshl_add_u64 v[216:217], s[44:45], 0, v[126:127]
	v_lshlrev_b64 v[216:217], 11, v[216:217]
	v_lshl_add_u64 v[216:217], v[134:135], 0, v[216:217]
	s_nop 0
	v_cvt_pk_bf16_f32 v100, v104, v105
	v_cvt_pk_bf16_f32 v101, v106, v107
	global_store_dwordx2 v[216:217], v[100:101], off nt
	s_waitcnt lgkmcnt(0)
	s_nop 1
	v_pk_mul_f32 v[208:209], v[240:241], v[200:201]
	v_pk_mul_f32 v[210:211], v[242:243], v[202:203]
	v_pk_mul_f32 v[212:213], v[240:241], v[204:205]
	v_pk_mul_f32 v[214:215], v[242:243], v[206:207]
	v_pk_fma_f32 v[140:141], v[140:141], v[96:97], v[208:209]
	v_pk_fma_f32 v[146:147], v[146:147], v[98:99], v[210:211]
	v_pk_fma_f32 v[144:145], v[144:145], v[96:97], v[212:213]
	v_pk_fma_f32 v[142:143], v[142:143], v[98:99], v[214:215]
	s_barrier
	ds_read_b128 v[96:99], v157
	ds_read_b128 v[200:203], v178 offset:41472
	ds_read_b128 v[204:207], v178 offset:41536
	ds_read_b128 v[208:211], v178 offset:41600
	ds_read_b128 v[212:215], v178 offset:41664
	ds_read_b128 v[216:219], v180 offset:58880
	ds_read_b128 v[184:187], v181 offset:58880
	ds_read_b128 v[220:223], v180 offset:58944
	ds_read_b128 v[188:191], v181 offset:58944
	ds_read_b128 v[224:227], v180 offset:59008
	ds_read_b128 v[192:195], v181 offset:59008
	ds_read_b128 v[228:231], v180 offset:59072
	ds_read_b128 v[196:199], v181 offset:59072
	s_min_u32 s14, s57, 0x79
	s_add_i32 s22, s14, 6
	s_lshl_b32 s14, s14, 6
	s_sub_i32 s44, 0x1e40, s14
	s_lshl_b32 s45, s22, 6
	s_and_b64 s[14:15], s[74:75], exec
	s_cselect_b32 s14, s45, s44
	s_ashr_i32 s15, s14, 31
	s_lshl_b64 s[14:15], s[14:15], 10
	s_add_u32 s14, s14, s56
	s_addc_u32 s15, s15, 0
	s_lshl_b64 s[14:15], s[14:15], 1
	s_mulk_i32 s22, 0x600
	s_waitcnt lgkmcnt(12)
	v_pk_mul_f32 v[108:109], v[140:141], v[96:97]
	v_pk_mul_f32 v[110:111], v[146:147], v[98:99]
	v_pk_mul_f32 v[112:113], v[144:145], v[96:97]
	v_pk_mul_f32 v[114:115], v[142:143], v[98:99]
	v_cvt_pk_bf16_f32 v108, v108, v109
	v_cvt_pk_bf16_f32 v109, v110, v111
	v_cvt_pk_bf16_f32 v112, v112, v113
	v_cvt_pk_bf16_f32 v113, v114, v115
	ds_write_b64 v177, v[108:109]
	ds_write_b64 v177, v[112:113] offset:4352
	s_waitcnt lgkmcnt(8)
	v_mfma_f32_16x16x32_bf16 v[100:103], v[216:219], v[200:203], 0
	v_mfma_f32_16x16x32_bf16 v[104:107], v[184:187], v[200:203], 0
	s_waitcnt lgkmcnt(6)
	v_mfma_f32_16x16x32_bf16 v[100:103], v[220:223], v[204:207], v[100:103]
	v_mfma_f32_16x16x32_bf16 v[104:107], v[188:191], v[204:207], v[104:107]
	s_waitcnt lgkmcnt(4)
	v_mfma_f32_16x16x32_bf16 v[100:103], v[224:227], v[208:211], v[100:103]
	v_mfma_f32_16x16x32_bf16 v[104:107], v[192:195], v[208:211], v[104:107]
	s_waitcnt lgkmcnt(2)
	v_mfma_f32_16x16x32_bf16 v[100:103], v[228:231], v[212:215], v[100:103]
	v_mfma_f32_16x16x32_bf16 v[104:107], v[196:199], v[212:215], v[104:107]
	s_waitcnt vmcnt(16)
	ds_write_b128 v148, v[24:27]
	ds_write_b128 v148, v[28:31] offset:8704
	ds_write_b128 v148, v[32:35] offset:17408
	ds_write_b128 v148, v[44:47] offset:26112
	s_and_saveexec_b64 s[44:45], s[6:7]
	s_cbranch_execz .Lscan_novv_1
	ds_write_b128 v151, v[36:39] offset:34816

.Lscan_vtj_1:
	ds_read_b128 v[240:243], v159
	s_waitcnt lgkmcnt(2)
	v_mfma_f32_16x16x32_bf16 v[200:203], v[108:111], v[184:187], 0
	v_mfma_f32_16x16x32_bf16 v[204:207], v[108:111], v[188:191], 0
	v_mfma_f32_16x16x32_bf16 v[200:203], v[112:115], v[192:195], v[200:203]
	v_mfma_f32_16x16x32_bf16 v[204:207], v[112:115], v[196:199], v[204:207]
	v_lshl_add_u64 v[216:217], s[44:45], 0, v[126:127]
	v_lshlrev_b64 v[216:217], 11, v[216:217]
	v_lshl_add_u64 v[216:217], v[134:135], 0, v[216:217]
	s_nop 0
	v_cvt_pk_bf16_f32 v100, v104, v105
	v_cvt_pk_bf16_f32 v101, v106, v107
	global_store_dwordx2 v[216:217], v[100:101], off nt
	s_waitcnt lgkmcnt(0)
	s_nop 1
	v_pk_mul_f32 v[208:209], v[240:241], v[200:201]
	v_pk_mul_f32 v[210:211], v[242:243], v[202:203]
	v_pk_mul_f32 v[212:213], v[240:241], v[204:205]
	v_pk_mul_f32 v[214:215], v[242:243], v[206:207]
	v_pk_fma_f32 v[140:141], v[140:141], v[96:97], v[208:209]
	v_pk_fma_f32 v[146:147], v[146:147], v[98:99], v[210:211]
	v_pk_fma_f32 v[144:145], v[144:145], v[96:97], v[212:213]
	v_pk_fma_f32 v[142:143], v[142:143], v[98:99], v[214:215]
	s_barrier
	ds_read_b128 v[96:99], v154 offset:39936
	ds_read_b128 v[200:203], v178
	ds_read_b128 v[204:207], v178 offset:64
	ds_read_b128 v[208:211], v178 offset:128
	ds_read_b128 v[212:215], v178 offset:192
	ds_read_b128 v[216:219], v180 offset:17408
	ds_read_b128 v[184:187], v181 offset:17408
	ds_read_b128 v[220:223], v180 offset:17472
	ds_read_b128 v[188:191], v181 offset:17472
	ds_read_b128 v[224:227], v180 offset:17536
	ds_read_b128 v[192:195], v181 offset:17536
	ds_read_b128 v[228:231], v180 offset:17600
	ds_read_b128 v[196:199], v181 offset:17600
	s_min_u32 s14, s57, 0x78
	s_add_i32 s22, s14, 7
	s_lshl_b32 s14, s14, 6
	s_sub_i32 s44, 0x1e00, s14
	s_lshl_b32 s45, s22, 6
	s_and_b64 s[14:15], s[74:75], exec
	s_cselect_b32 s14, s45, s44
	s_ashr_i32 s15, s14, 31
	s_lshl_b64 s[14:15], s[14:15], 10
	s_add_u32 s14, s14, s56
	s_addc_u32 s15, s15, 0
	s_lshl_b64 s[14:15], s[14:15], 1
	s_mulk_i32 s22, 0x600
	s_waitcnt lgkmcnt(12)
	v_pk_mul_f32 v[108:109], v[140:141], v[96:97]
	v_pk_mul_f32 v[110:111], v[146:147], v[98:99]
	v_pk_mul_f32 v[112:113], v[144:145], v[96:97]
	v_pk_mul_f32 v[114:115], v[142:143], v[98:99]
	v_cvt_pk_bf16_f32 v108, v108, v109
	v_cvt_pk_bf16_f32 v109, v110, v111
	v_cvt_pk_bf16_f32 v112, v112, v113
	v_cvt_pk_bf16_f32 v113, v114, v115
	ds_write_b64 v177, v[108:109]
	ds_write_b64 v177, v[112:113] offset:4352
	s_waitcnt lgkmcnt(8)
	v_mfma_f32_16x16x32_bf16 v[100:103], v[216:219], v[200:203], 0
	v_mfma_f32_16x16x32_bf16 v[104:107], v[184:187], v[200:203], 0
	s_waitcnt lgkmcnt(6)
	v_mfma_f32_16x16x32_bf16 v[100:103], v[220:223], v[204:207], v[100:103]
	v_mfma_f32_16x16x32_bf16 v[104:107], v[188:191], v[204:207], v[104:107]
	s_waitcnt lgkmcnt(4)
	v_mfma_f32_16x16x32_bf16 v[100:103], v[224:227], v[208:211], v[100:103]
	v_mfma_f32_16x16x32_bf16 v[104:107], v[192:195], v[208:211], v[104:107]
	s_waitcnt lgkmcnt(2)
	v_mfma_f32_16x16x32_bf16 v[100:103], v[228:231], v[212:215], v[100:103]
	v_mfma_f32_16x16x32_bf16 v[104:107], v[196:199], v[212:215], v[104:107]
	s_waitcnt vmcnt(16)
	ds_write_b128 v148, v[48:51] offset:41472
	ds_write_b128 v148, v[52:55] offset:50176
	ds_write_b128 v148, v[56:59] offset:58880
	ds_write_b128 v153, v[60:63] offset:8704
	s_and_saveexec_b64 s[44:45], s[6:7]
	s_cbranch_execz .Lscan_novv_2
	ds_write_b128 v176, v[64:67]

.Lscan_vtj_2:
	ds_read_b128 v[240:243], v154 offset:40960
	s_waitcnt lgkmcnt(2)
	v_mfma_f32_16x16x32_bf16 v[200:203], v[108:111], v[184:187], 0
	v_mfma_f32_16x16x32_bf16 v[204:207], v[108:111], v[188:191], 0
	v_mfma_f32_16x16x32_bf16 v[200:203], v[112:115], v[192:195], v[200:203]
	v_mfma_f32_16x16x32_bf16 v[204:207], v[112:115], v[196:199], v[204:207]
	v_lshl_add_u64 v[216:217], s[44:45], 0, v[126:127]
	v_lshlrev_b64 v[216:217], 11, v[216:217]
	v_lshl_add_u64 v[216:217], v[134:135], 0, v[216:217]
	s_nop 0
	v_cvt_pk_bf16_f32 v100, v104, v105
	v_cvt_pk_bf16_f32 v101, v106, v107
	global_store_dwordx2 v[216:217], v[100:101], off nt
	s_waitcnt lgkmcnt(0)
	s_nop 1
	v_pk_mul_f32 v[208:209], v[240:241], v[200:201]
	v_pk_mul_f32 v[210:211], v[242:243], v[202:203]
	v_pk_mul_f32 v[212:213], v[240:241], v[204:205]
	v_pk_mul_f32 v[214:215], v[242:243], v[206:207]
	v_pk_fma_f32 v[140:141], v[140:141], v[96:97], v[208:209]
	v_pk_fma_f32 v[146:147], v[146:147], v[98:99], v[210:211]
	v_pk_fma_f32 v[144:145], v[144:145], v[96:97], v[212:213]
	v_pk_fma_f32 v[142:143], v[142:143], v[98:99], v[214:215]
	s_barrier
	ds_read_b128 v[96:99], v157
	ds_read_b128 v[200:203], v178 offset:41472
	ds_read_b128 v[204:207], v178 offset:41536
	ds_read_b128 v[208:211], v178 offset:41600
	ds_read_b128 v[212:215], v178 offset:41664
	ds_read_b128 v[216:219], v180 offset:58880
	ds_read_b128 v[184:187], v181 offset:58880
	ds_read_b128 v[220:223], v180 offset:58944
	ds_read_b128 v[188:191], v181 offset:58944
	ds_read_b128 v[224:227], v180 offset:59008
	ds_read_b128 v[192:195], v181 offset:59008
	ds_read_b128 v[228:231], v180 offset:59072
	ds_read_b128 v[196:199], v181 offset:59072
	s_min_u32 s14, s57, 0x77
	s_add_i32 s22, s14, 8
	s_lshl_b32 s14, s14, 6
	s_sub_i32 s44, 0x1dc0, s14
	s_lshl_b32 s45, s22, 6
	s_and_b64 s[14:15], s[74:75], exec
	s_cselect_b32 s14, s45, s44
	s_ashr_i32 s15, s14, 31
	s_lshl_b64 s[14:15], s[14:15], 10
	s_add_u32 s14, s14, s56
	s_addc_u32 s15, s15, 0
	s_lshl_b64 s[14:15], s[14:15], 1
	s_mulk_i32 s22, 0x600
	s_waitcnt lgkmcnt(12)
	v_pk_mul_f32 v[108:109], v[140:141], v[96:97]
	v_pk_mul_f32 v[110:111], v[146:147], v[98:99]
	v_pk_mul_f32 v[112:113], v[144:145], v[96:97]
	v_pk_mul_f32 v[114:115], v[142:143], v[98:99]
	v_cvt_pk_bf16_f32 v108, v108, v109
	v_cvt_pk_bf16_f32 v109, v110, v111
	v_cvt_pk_bf16_f32 v112, v112, v113
	v_cvt_pk_bf16_f32 v113, v114, v115
	ds_write_b64 v177, v[108:109]
	ds_write_b64 v177, v[112:113] offset:4352
	s_waitcnt lgkmcnt(8)
	v_mfma_f32_16x16x32_bf16 v[100:103], v[216:219], v[200:203], 0
	v_mfma_f32_16x16x32_bf16 v[104:107], v[184:187], v[200:203], 0
	s_waitcnt lgkmcnt(6)
	v_mfma_f32_16x16x32_bf16 v[100:103], v[220:223], v[204:207], v[100:103]
	v_mfma_f32_16x16x32_bf16 v[104:107], v[188:191], v[204:207], v[104:107]
	s_waitcnt lgkmcnt(4)
	v_mfma_f32_16x16x32_bf16 v[100:103], v[224:227], v[208:211], v[100:103]
	v_mfma_f32_16x16x32_bf16 v[104:107], v[192:195], v[208:211], v[104:107]
	s_waitcnt lgkmcnt(2)
	v_mfma_f32_16x16x32_bf16 v[100:103], v[228:231], v[212:215], v[100:103]
	v_mfma_f32_16x16x32_bf16 v[104:107], v[196:199], v[212:215], v[104:107]
	s_waitcnt vmcnt(16)
	ds_write_b128 v148, v[72:75]
	ds_write_b128 v148, v[76:79] offset:8704
	ds_write_b128 v148, v[80:83] offset:17408
	ds_write_b128 v148, v[84:87] offset:26112
	s_and_saveexec_b64 s[44:45], s[6:7]
	s_cbranch_execz .Lscan_novv_3
	ds_write_b128 v151, v[88:91] offset:34816

.Lscan_vtj_3:
	ds_read_b128 v[240:243], v159
	s_waitcnt lgkmcnt(2)
	v_mfma_f32_16x16x32_bf16 v[200:203], v[108:111], v[184:187], 0
	v_mfma_f32_16x16x32_bf16 v[204:207], v[108:111], v[188:191], 0
	v_mfma_f32_16x16x32_bf16 v[200:203], v[112:115], v[192:195], v[200:203]
	v_mfma_f32_16x16x32_bf16 v[204:207], v[112:115], v[196:199], v[204:207]
	v_lshl_add_u64 v[216:217], s[44:45], 0, v[126:127]
	v_lshlrev_b64 v[216:217], 11, v[216:217]
	v_lshl_add_u64 v[216:217], v[134:135], 0, v[216:217]
	s_nop 0
	v_cvt_pk_bf16_f32 v100, v104, v105
	v_cvt_pk_bf16_f32 v101, v106, v107
	global_store_dwordx2 v[216:217], v[100:101], off nt
	s_waitcnt lgkmcnt(0)
	s_nop 1
	v_pk_mul_f32 v[208:209], v[240:241], v[200:201]
	v_pk_mul_f32 v[210:211], v[242:243], v[202:203]
	v_pk_mul_f32 v[212:213], v[240:241], v[204:205]
	v_pk_mul_f32 v[214:215], v[242:243], v[206:207]
	v_pk_fma_f32 v[140:141], v[140:141], v[96:97], v[208:209]
	v_pk_fma_f32 v[146:147], v[146:147], v[98:99], v[210:211]
	v_pk_fma_f32 v[144:145], v[144:145], v[96:97], v[212:213]
	v_pk_fma_f32 v[142:143], v[142:143], v[98:99], v[214:215]
	s_barrier
	s_addk_i32 s58, 0x100
	s_addk_i32 s59, 0xff00
	s_cmpk_gt_u32 s57, 0x7b
	s_cbranch_scc0 .Lscan_head
	s_branch .LBB0_609
